# x-row rmsnorm v2: each workgroup stays inside one batch, 4-deep ring of 2-row buffers with counted vmcnt; phase-2 GEMM epilogue stores write-through (sc1) so the grid-barrier L2 write-back is shorter
# baseline (speedup 1.0000x reference)
.LBB0_173:
	s_andn2_b64 vcc, exec, s[4:5]
	s_cbranch_vccnz .LBB0_179
	s_cmp_lt_u32 s81, 32
	s_cbranch_scc1 .LBB0_179
	s_sub_u32 s2, s81, 32
	s_mul_i32 s4, s2, 0x925
	s_lshr_b32 s4, s4, 16
	s_mul_i32 s5, s4, 28
	s_sub_u32 s5, s2, s5
	s_lshl_b32 s2, s4, 8
	s_add_u32 s2, s2, s5
	s_cmp_lt_u32 s5, 4
	s_cselect_b32 s26, 1, 0
	v_readfirstlane_b32 s3, v205
	v_lshlrev_b32_e32 v194, 4, v192
	v_lshlrev_b32_e32 v196, 3, v192
	v_mbcnt_hi_u32_b32 v197, -1, v207
	v_readlane_b32 s18, v241, 2
	v_readlane_b32 s19, v241, 3
	v_add_u32_e32 v195, 0x1000, v194
	v_xor_b32_e32 v198, 32, v197
	v_lshlrev_b32_e32 v198, 2, v198
	v_xor_b32_e32 v199, 16, v197
	v_lshlrev_b32_e32 v199, 2, v199
	v_xor_b32_e32 v200, 8, v197
	v_lshlrev_b32_e32 v200, 2, v200
	v_xor_b32_e32 v201, 4, v197
	v_lshlrev_b32_e32 v201, 2, v201
	v_xor_b32_e32 v202, 2, v197
	v_lshlrev_b32_e32 v202, 2, v202
	v_xor_b32_e32 v203, 1, v197
	v_lshlrev_b32_e32 v203, 2, v203
	v_mov_b32_e32 v208, 0x358637bd
	s_mov_b32 s27, 0x800000
	s_lshl_b32 s3, s3, 1
	s_lshl_b32 s2, s2, 4
	s_add_u32 s2, s2, s3
	s_lshl_b32 s5, s2, 12
	s_add_u32 s14, s52, s5
	s_addc_u32 s15, s53, 0
	s_lshl_b32 s5, s2, 11
	s_add_u32 s10, s94, s5
	s_addc_u32 s11, s95, 0
	s_mul_i32 s4, s4, 0x3000
	s_add_u32 s16, s18, s4
	s_addc_u32 s17, s19, 0
	global_load_dwordx4 v[0:3], v194, s[60:61]
	global_load_dwordx4 v[4:7], v194, s[60:61] offset:1024
	global_load_dwordx4 v[8:11], v194, s[60:61] offset:2048
	global_load_dwordx4 v[12:15], v194, s[60:61] offset:3072
	global_load_dwordx4 v[160:163], v194, s[16:17]
	global_load_dwordx4 v[164:167], v194, s[16:17] offset:1024
	global_load_dwordx4 v[168:171], v194, s[16:17] offset:2048
	global_load_dwordx4 v[172:175], v194, s[16:17] offset:3072
	global_load_dwordx4 v[144:147], v195, s[16:17]
	global_load_dwordx4 v[148:151], v195, s[16:17] offset:1024
	global_load_dwordx4 v[152:155], v195, s[16:17] offset:2048
	global_load_dwordx4 v[156:159], v195, s[16:17] offset:3072
	global_load_dwordx4 v[16:19], v194, s[14:15]
	global_load_dwordx4 v[20:23], v194, s[14:15] offset:1024
	global_load_dwordx4 v[24:27], v194, s[14:15] offset:2048
	global_load_dwordx4 v[28:31], v194, s[14:15] offset:3072
	global_load_dwordx4 v[32:35], v195, s[14:15]
	global_load_dwordx4 v[36:39], v195, s[14:15] offset:1024
	global_load_dwordx4 v[40:43], v195, s[14:15] offset:2048
	global_load_dwordx4 v[44:47], v195, s[14:15] offset:3072
	s_add_u32 s14, s14, 0x1c0000
	s_addc_u32 s15, s15, 0
	global_load_dwordx4 v[48:51], v194, s[14:15]
	global_load_dwordx4 v[52:55], v194, s[14:15] offset:1024
	global_load_dwordx4 v[56:59], v194, s[14:15] offset:2048
	global_load_dwordx4 v[60:63], v194, s[14:15] offset:3072
	global_load_dwordx4 v[64:67], v195, s[14:15]
	global_load_dwordx4 v[68:71], v195, s[14:15] offset:1024
	global_load_dwordx4 v[72:75], v195, s[14:15] offset:2048
	global_load_dwordx4 v[76:79], v195, s[14:15] offset:3072
	s_add_u32 s14, s14, 0x1c0000
	s_addc_u32 s15, s15, 0
	global_load_dwordx4 v[80:83], v194, s[14:15]
	global_load_dwordx4 v[84:87], v194, s[14:15] offset:1024
	global_load_dwordx4 v[88:91], v194, s[14:15] offset:2048
	global_load_dwordx4 v[92:95], v194, s[14:15] offset:3072
	global_load_dwordx4 v[96:99], v195, s[14:15]
	global_load_dwordx4 v[100:103], v195, s[14:15] offset:1024
	global_load_dwordx4 v[104:107], v195, s[14:15] offset:2048
	global_load_dwordx4 v[108:111], v195, s[14:15] offset:3072
	s_add_u32 s14, s14, 0x1c0000
	s_addc_u32 s15, s15, 0
	global_load_dwordx4 v[112:115], v194, s[14:15]
	global_load_dwordx4 v[116:119], v194, s[14:15] offset:1024
	global_load_dwordx4 v[120:123], v194, s[14:15] offset:2048
	global_load_dwordx4 v[124:127], v194, s[14:15] offset:3072
	global_load_dwordx4 v[128:131], v195, s[14:15]
	global_load_dwordx4 v[132:135], v195, s[14:15] offset:1024
	global_load_dwordx4 v[136:139], v195, s[14:15] offset:2048
	global_load_dwordx4 v[140:143], v195, s[14:15] offset:3072
	s_waitcnt vmcnt(32)
	v_add_f32_e32 v144, 1.0, v144
	v_add_f32_e32 v145, 1.0, v145
	v_add_f32_e32 v146, 1.0, v146
	v_add_f32_e32 v147, 1.0, v147
	v_add_f32_e32 v148, 1.0, v148
	v_add_f32_e32 v149, 1.0, v149
	v_add_f32_e32 v150, 1.0, v150
	v_add_f32_e32 v151, 1.0, v151
	v_add_f32_e32 v152, 1.0, v152
	v_add_f32_e32 v153, 1.0, v153
	v_add_f32_e32 v154, 1.0, v154
	v_add_f32_e32 v155, 1.0, v155
	v_add_f32_e32 v156, 1.0, v156
	v_add_f32_e32 v157, 1.0, v157
	v_add_f32_e32 v158, 1.0, v158
	v_add_f32_e32 v159, 1.0, v159
	s_waitcnt vmcnt(24)
	v_pk_mul_f32 v[178:179], v[16:17], v[16:17]
	v_pk_fma_f32 v[178:179], v[18:19], v[18:19], v[178:179]
	v_pk_fma_f32 v[178:179], v[20:21], v[20:21], v[178:179]
	v_pk_fma_f32 v[178:179], v[22:23], v[22:23], v[178:179]
	v_pk_fma_f32 v[178:179], v[24:25], v[24:25], v[178:179]
	v_pk_fma_f32 v[178:179], v[26:27], v[26:27], v[178:179]
	v_pk_fma_f32 v[178:179], v[28:29], v[28:29], v[178:179]
	v_pk_fma_f32 v[178:179], v[30:31], v[30:31], v[178:179]
	v_pk_mul_f32 v[180:181], v[32:33], v[32:33]
	v_pk_fma_f32 v[180:181], v[34:35], v[34:35], v[180:181]
	v_pk_fma_f32 v[180:181], v[36:37], v[36:37], v[180:181]
	v_pk_fma_f32 v[180:181], v[38:39], v[38:39], v[180:181]
	v_pk_fma_f32 v[180:181], v[40:41], v[40:41], v[180:181]
	v_pk_fma_f32 v[180:181], v[42:43], v[42:43], v[180:181]
	v_pk_fma_f32 v[180:181], v[44:45], v[44:45], v[180:181]
	v_pk_fma_f32 v[180:181], v[46:47], v[46:47], v[180:181]
	v_add_f32_e32 v176, v178, v179
	v_add_f32_e32 v177, v180, v181
	ds_bpermute_b32 v178, v198, v176
	ds_bpermute_b32 v179, v198, v177
	s_waitcnt lgkmcnt(0)
	v_add_f32_e32 v176, v176, v178
	v_add_f32_e32 v177, v177, v179
	ds_bpermute_b32 v178, v199, v176
	ds_bpermute_b32 v179, v199, v177
	s_waitcnt lgkmcnt(0)
	v_add_f32_e32 v176, v176, v178
	v_add_f32_e32 v177, v177, v179
	ds_bpermute_b32 v178, v200, v176
	ds_bpermute_b32 v179, v200, v177
	s_waitcnt lgkmcnt(0)
	v_add_f32_e32 v176, v176, v178
	v_add_f32_e32 v177, v177, v179
	ds_bpermute_b32 v178, v201, v176
	ds_bpermute_b32 v179, v201, v177
	s_waitcnt lgkmcnt(0)
	v_add_f32_e32 v176, v176, v178
	v_add_f32_e32 v177, v177, v179
	ds_bpermute_b32 v178, v202, v176
	ds_bpermute_b32 v179, v202, v177
	s_waitcnt lgkmcnt(0)
	v_add_f32_e32 v176, v176, v178
	v_add_f32_e32 v177, v177, v179
	ds_bpermute_b32 v178, v203, v176
	ds_bpermute_b32 v179, v203, v177
	s_waitcnt lgkmcnt(0)
	v_add_f32_e32 v176, v176, v178
	v_add_f32_e32 v177, v177, v179
	v_fmamk_f32 v176, v176, 0x3a800000, v208
	v_mul_f32_e32 v178, 0x4b800000, v176
	v_cmp_gt_f32_e32 vcc, s27, v176
	s_nop 1
	v_cndmask_b32_e32 v176, v176, v178, vcc
	v_rsq_f32_e32 v209, v176
	s_nop 0
	v_mul_f32_e32 v178, 0x45800000, v209
	v_cndmask_b32_e32 v209, v209, v178, vcc
	v_fmamk_f32 v177, v177, 0x3a800000, v208
	v_mul_f32_e32 v178, 0x4b800000, v177
	v_cmp_gt_f32_e32 vcc, s27, v177
	s_nop 1
	v_cndmask_b32_e32 v177, v177, v178, vcc
	v_rsq_f32_e32 v210, v177
	s_nop 0
	v_mul_f32_e32 v178, 0x45800000, v210
	v_cndmask_b32_e32 v210, v210, v178, vcc
	v_mul_f32_e32 v16, v16, v209
	v_mul_f32_e32 v16, v0, v16
	v_fma_f32 v16, v144, v16, v160
	v_mul_f32_e32 v17, v17, v209
	v_mul_f32_e32 v17, v1, v17
	v_fma_f32 v17, v145, v17, v161
	v_mul_f32_e32 v18, v18, v209
	v_mul_f32_e32 v18, v2, v18
	v_fma_f32 v18, v146, v18, v162
	v_mul_f32_e32 v19, v19, v209
	v_mul_f32_e32 v19, v3, v19
	v_fma_f32 v19, v147, v19, v163
	v_cvt_pk_bf16_f32 v180, v16, v17
	v_cvt_pk_bf16_f32 v181, v18, v19
	global_store_dwordx2 v196, v[180:181], s[10:11]
	s_nop 0
	v_mul_f32_e32 v20, v20, v209
	v_mul_f32_e32 v20, v4, v20
	v_fma_f32 v20, v148, v20, v164
	v_mul_f32_e32 v21, v21, v209
	v_mul_f32_e32 v21, v5, v21
	v_fma_f32 v21, v149, v21, v165
	v_mul_f32_e32 v22, v22, v209
	v_mul_f32_e32 v22, v6, v22
	v_fma_f32 v22, v150, v22, v166
	v_mul_f32_e32 v23, v23, v209
	v_mul_f32_e32 v23, v7, v23
	v_fma_f32 v23, v151, v23, v167
	v_cvt_pk_bf16_f32 v180, v20, v21
	v_cvt_pk_bf16_f32 v181, v22, v23
	global_store_dwordx2 v196, v[180:181], s[10:11] offset:512
	s_nop 0
	v_mul_f32_e32 v24, v24, v209
	v_mul_f32_e32 v24, v8, v24
	v_fma_f32 v24, v152, v24, v168
	v_mul_f32_e32 v25, v25, v209
	v_mul_f32_e32 v25, v9, v25
	v_fma_f32 v25, v153, v25, v169
	v_mul_f32_e32 v26, v26, v209
	v_mul_f32_e32 v26, v10, v26
	v_fma_f32 v26, v154, v26, v170
	v_mul_f32_e32 v27, v27, v209
	v_mul_f32_e32 v27, v11, v27
	v_fma_f32 v27, v155, v27, v171
	v_cvt_pk_bf16_f32 v180, v24, v25
	v_cvt_pk_bf16_f32 v181, v26, v27
	global_store_dwordx2 v196, v[180:181], s[10:11] offset:1024
	s_nop 0
	v_mul_f32_e32 v28, v28, v209
	v_mul_f32_e32 v28, v12, v28
	v_fma_f32 v28, v156, v28, v172
	v_mul_f32_e32 v29, v29, v209
	v_mul_f32_e32 v29, v13, v29
	v_fma_f32 v29, v157, v29, v173
	v_mul_f32_e32 v30, v30, v209
	v_mul_f32_e32 v30, v14, v30
	v_fma_f32 v30, v158, v30, v174
	v_mul_f32_e32 v31, v31, v209
	v_mul_f32_e32 v31, v15, v31
	v_fma_f32 v31, v159, v31, v175
	v_cvt_pk_bf16_f32 v180, v28, v29
	v_cvt_pk_bf16_f32 v181, v30, v31
	global_store_dwordx2 v196, v[180:181], s[10:11] offset:1536
	s_nop 0
	v_mul_f32_e32 v32, v32, v210
	v_mul_f32_e32 v32, v0, v32
	v_fma_f32 v32, v144, v32, v160
	v_mul_f32_e32 v33, v33, v210
	v_mul_f32_e32 v33, v1, v33
	v_fma_f32 v33, v145, v33, v161
	v_mul_f32_e32 v34, v34, v210
	v_mul_f32_e32 v34, v2, v34
	v_fma_f32 v34, v146, v34, v162
	v_mul_f32_e32 v35, v35, v210
	v_mul_f32_e32 v35, v3, v35
	v_fma_f32 v35, v147, v35, v163
	v_cvt_pk_bf16_f32 v180, v32, v33
	v_cvt_pk_bf16_f32 v181, v34, v35
	global_store_dwordx2 v196, v[180:181], s[10:11] offset:2048
	s_nop 0
	v_mul_f32_e32 v36, v36, v210
	v_mul_f32_e32 v36, v4, v36
	v_fma_f32 v36, v148, v36, v164
	v_mul_f32_e32 v37, v37, v210
	v_mul_f32_e32 v37, v5, v37
	v_fma_f32 v37, v149, v37, v165
	v_mul_f32_e32 v38, v38, v210
	v_mul_f32_e32 v38, v6, v38
	v_fma_f32 v38, v150, v38, v166
	v_mul_f32_e32 v39, v39, v210
	v_mul_f32_e32 v39, v7, v39
	v_fma_f32 v39, v151, v39, v167
	v_cvt_pk_bf16_f32 v180, v36, v37
	v_cvt_pk_bf16_f32 v181, v38, v39
	global_store_dwordx2 v196, v[180:181], s[10:11] offset:2560
	s_nop 0
	v_mul_f32_e32 v40, v40, v210
	v_mul_f32_e32 v40, v8, v40
	v_fma_f32 v40, v152, v40, v168
	v_mul_f32_e32 v41, v41, v210
	v_mul_f32_e32 v41, v9, v41
	v_fma_f32 v41, v153, v41, v169
	v_mul_f32_e32 v42, v42, v210
	v_mul_f32_e32 v42, v10, v42
	v_fma_f32 v42, v154, v42, v170
	v_mul_f32_e32 v43, v43, v210
	v_mul_f32_e32 v43, v11, v43
	v_fma_f32 v43, v155, v43, v171
	v_cvt_pk_bf16_f32 v180, v40, v41
	v_cvt_pk_bf16_f32 v181, v42, v43
	global_store_dwordx2 v196, v[180:181], s[10:11] offset:3072
	s_nop 0
	v_mul_f32_e32 v44, v44, v210
	v_mul_f32_e32 v44, v12, v44
	v_fma_f32 v44, v156, v44, v172
	v_mul_f32_e32 v45, v45, v210
	v_mul_f32_e32 v45, v13, v45
	v_fma_f32 v45, v157, v45, v173
	v_mul_f32_e32 v46, v46, v210
	v_mul_f32_e32 v46, v14, v46
	v_fma_f32 v46, v158, v46, v174
	v_mul_f32_e32 v47, v47, v210
	v_mul_f32_e32 v47, v15, v47
	v_fma_f32 v47, v159, v47, v175
	v_cvt_pk_bf16_f32 v180, v44, v45
	v_cvt_pk_bf16_f32 v181, v46, v47
	global_store_dwordx2 v196, v[180:181], s[10:11] offset:3584
	s_nop 0
	s_add_u32 s14, s14, 0x1c0000
	s_addc_u32 s15, s15, 0
	global_load_dwordx4 v[16:19], v194, s[14:15]
	global_load_dwordx4 v[20:23], v194, s[14:15] offset:1024
	global_load_dwordx4 v[24:27], v194, s[14:15] offset:2048
	global_load_dwordx4 v[28:31], v194, s[14:15] offset:3072
	global_load_dwordx4 v[32:35], v195, s[14:15]
	global_load_dwordx4 v[36:39], v195, s[14:15] offset:1024
	global_load_dwordx4 v[40:43], v195, s[14:15] offset:2048
	global_load_dwordx4 v[44:47], v195, s[14:15] offset:3072
	s_waitcnt vmcnt(32)
	s_add_u32 s10, s10, 0xe0000
	s_addc_u32 s11, s11, 0
	v_pk_mul_f32 v[178:179], v[48:49], v[48:49]
	v_pk_fma_f32 v[178:179], v[50:51], v[50:51], v[178:179]
	v_pk_fma_f32 v[178:179], v[52:53], v[52:53], v[178:179]
	v_pk_fma_f32 v[178:179], v[54:55], v[54:55], v[178:179]
	v_pk_fma_f32 v[178:179], v[56:57], v[56:57], v[178:179]
	v_pk_fma_f32 v[178:179], v[58:59], v[58:59], v[178:179]
	v_pk_fma_f32 v[178:179], v[60:61], v[60:61], v[178:179]
	v_pk_fma_f32 v[178:179], v[62:63], v[62:63], v[178:179]
	v_pk_mul_f32 v[180:181], v[64:65], v[64:65]
	v_pk_fma_f32 v[180:181], v[66:67], v[66:67], v[180:181]
	v_pk_fma_f32 v[180:181], v[68:69], v[68:69], v[180:181]
	v_pk_fma_f32 v[180:181], v[70:71], v[70:71], v[180:181]
	v_pk_fma_f32 v[180:181], v[72:73], v[72:73], v[180:181]
	v_pk_fma_f32 v[180:181], v[74:75], v[74:75], v[180:181]
	v_pk_fma_f32 v[180:181], v[76:77], v[76:77], v[180:181]
	v_pk_fma_f32 v[180:181], v[78:79], v[78:79], v[180:181]
	v_add_f32_e32 v176, v178, v179
	v_add_f32_e32 v177, v180, v181
	ds_bpermute_b32 v178, v198, v176
	ds_bpermute_b32 v179, v198, v177
	s_waitcnt lgkmcnt(0)
	v_add_f32_e32 v176, v176, v178
	v_add_f32_e32 v177, v177, v179
	ds_bpermute_b32 v178, v199, v176
	ds_bpermute_b32 v179, v199, v177
	s_waitcnt lgkmcnt(0)
	v_add_f32_e32 v176, v176, v178
	v_add_f32_e32 v177, v177, v179
	ds_bpermute_b32 v178, v200, v176
	ds_bpermute_b32 v179, v200, v177
	s_waitcnt lgkmcnt(0)
	v_add_f32_e32 v176, v176, v178
	v_add_f32_e32 v177, v177, v179
	ds_bpermute_b32 v178, v201, v176
	ds_bpermute_b32 v179, v201, v177
	s_waitcnt lgkmcnt(0)
	v_add_f32_e32 v176, v176, v178
	v_add_f32_e32 v177, v177, v179
	ds_bpermute_b32 v178, v202, v176
	ds_bpermute_b32 v179, v202, v177
	s_waitcnt lgkmcnt(0)
	v_add_f32_e32 v176, v176, v178
	v_add_f32_e32 v177, v177, v179
	ds_bpermute_b32 v178, v203, v176
	ds_bpermute_b32 v179, v203, v177
	s_waitcnt lgkmcnt(0)
	v_add_f32_e32 v176, v176, v178
	v_add_f32_e32 v177, v177, v179
	v_fmamk_f32 v176, v176, 0x3a800000, v208
	v_mul_f32_e32 v178, 0x4b800000, v176
	v_cmp_gt_f32_e32 vcc, s27, v176
	s_nop 1
	v_cndmask_b32_e32 v176, v176, v178, vcc
	v_rsq_f32_e32 v209, v176
	s_nop 0
	v_mul_f32_e32 v178, 0x45800000, v209
	v_cndmask_b32_e32 v209, v209, v178, vcc
	v_fmamk_f32 v177, v177, 0x3a800000, v208
	v_mul_f32_e32 v178, 0x4b800000, v177
	v_cmp_gt_f32_e32 vcc, s27, v177
	s_nop 1
	v_cndmask_b32_e32 v177, v177, v178, vcc
	v_rsq_f32_e32 v210, v177
	s_nop 0
	v_mul_f32_e32 v178, 0x45800000, v210
	v_cndmask_b32_e32 v210, v210, v178, vcc
	v_mul_f32_e32 v48, v48, v209
	v_mul_f32_e32 v48, v0, v48
	v_fma_f32 v48, v144, v48, v160
	v_mul_f32_e32 v49, v49, v209
	v_mul_f32_e32 v49, v1, v49
	v_fma_f32 v49, v145, v49, v161
	v_mul_f32_e32 v50, v50, v209
	v_mul_f32_e32 v50, v2, v50
	v_fma_f32 v50, v146, v50, v162
	v_mul_f32_e32 v51, v51, v209
	v_mul_f32_e32 v51, v3, v51
	v_fma_f32 v51, v147, v51, v163
	v_cvt_pk_bf16_f32 v180, v48, v49
	v_cvt_pk_bf16_f32 v181, v50, v51
	global_store_dwordx2 v196, v[180:181], s[10:11]
	s_nop 0
	v_mul_f32_e32 v52, v52, v209
	v_mul_f32_e32 v52, v4, v52
	v_fma_f32 v52, v148, v52, v164
	v_mul_f32_e32 v53, v53, v209
	v_mul_f32_e32 v53, v5, v53
	v_fma_f32 v53, v149, v53, v165
	v_mul_f32_e32 v54, v54, v209
	v_mul_f32_e32 v54, v6, v54
	v_fma_f32 v54, v150, v54, v166
	v_mul_f32_e32 v55, v55, v209
	v_mul_f32_e32 v55, v7, v55
	v_fma_f32 v55, v151, v55, v167
	v_cvt_pk_bf16_f32 v180, v52, v53
	v_cvt_pk_bf16_f32 v181, v54, v55
	global_store_dwordx2 v196, v[180:181], s[10:11] offset:512
	s_nop 0
	v_mul_f32_e32 v56, v56, v209
	v_mul_f32_e32 v56, v8, v56
	v_fma_f32 v56, v152, v56, v168
	v_mul_f32_e32 v57, v57, v209
	v_mul_f32_e32 v57, v9, v57
	v_fma_f32 v57, v153, v57, v169
	v_mul_f32_e32 v58, v58, v209
	v_mul_f32_e32 v58, v10, v58
	v_fma_f32 v58, v154, v58, v170
	v_mul_f32_e32 v59, v59, v209
	v_mul_f32_e32 v59, v11, v59
	v_fma_f32 v59, v155, v59, v171
	v_cvt_pk_bf16_f32 v180, v56, v57
	v_cvt_pk_bf16_f32 v181, v58, v59
	global_store_dwordx2 v196, v[180:181], s[10:11] offset:1024
	s_nop 0
	v_mul_f32_e32 v60, v60, v209
	v_mul_f32_e32 v60, v12, v60
	v_fma_f32 v60, v156, v60, v172
	v_mul_f32_e32 v61, v61, v209
	v_mul_f32_e32 v61, v13, v61
	v_fma_f32 v61, v157, v61, v173
	v_mul_f32_e32 v62, v62, v209
	v_mul_f32_e32 v62, v14, v62
	v_fma_f32 v62, v158, v62, v174
	v_mul_f32_e32 v63, v63, v209
	v_mul_f32_e32 v63, v15, v63
	v_fma_f32 v63, v159, v63, v175
	v_cvt_pk_bf16_f32 v180, v60, v61
	v_cvt_pk_bf16_f32 v181, v62, v63
	global_store_dwordx2 v196, v[180:181], s[10:11] offset:1536
	s_nop 0
	v_mul_f32_e32 v64, v64, v210
	v_mul_f32_e32 v64, v0, v64
	v_fma_f32 v64, v144, v64, v160
	v_mul_f32_e32 v65, v65, v210
	v_mul_f32_e32 v65, v1, v65
	v_fma_f32 v65, v145, v65, v161
	v_mul_f32_e32 v66, v66, v210
	v_mul_f32_e32 v66, v2, v66
	v_fma_f32 v66, v146, v66, v162
	v_mul_f32_e32 v67, v67, v210
	v_mul_f32_e32 v67, v3, v67
	v_fma_f32 v67, v147, v67, v163
	v_cvt_pk_bf16_f32 v180, v64, v65
	v_cvt_pk_bf16_f32 v181, v66, v67
	global_store_dwordx2 v196, v[180:181], s[10:11] offset:2048
	s_nop 0
	v_mul_f32_e32 v68, v68, v210
	v_mul_f32_e32 v68, v4, v68
	v_fma_f32 v68, v148, v68, v164
	v_mul_f32_e32 v69, v69, v210
	v_mul_f32_e32 v69, v5, v69
	v_fma_f32 v69, v149, v69, v165
	v_mul_f32_e32 v70, v70, v210
	v_mul_f32_e32 v70, v6, v70
	v_fma_f32 v70, v150, v70, v166
	v_mul_f32_e32 v71, v71, v210
	v_mul_f32_e32 v71, v7, v71
	v_fma_f32 v71, v151, v71, v167
	v_cvt_pk_bf16_f32 v180, v68, v69
	v_cvt_pk_bf16_f32 v181, v70, v71
	global_store_dwordx2 v196, v[180:181], s[10:11] offset:2560
	s_nop 0
	v_mul_f32_e32 v72, v72, v210
	v_mul_f32_e32 v72, v8, v72
	v_fma_f32 v72, v152, v72, v168
	v_mul_f32_e32 v73, v73, v210
	v_mul_f32_e32 v73, v9, v73
	v_fma_f32 v73, v153, v73, v169
	v_mul_f32_e32 v74, v74, v210
	v_mul_f32_e32 v74, v10, v74
	v_fma_f32 v74, v154, v74, v170
	v_mul_f32_e32 v75, v75, v210
	v_mul_f32_e32 v75, v11, v75
	v_fma_f32 v75, v155, v75, v171
	v_cvt_pk_bf16_f32 v180, v72, v73
	v_cvt_pk_bf16_f32 v181, v74, v75
	global_store_dwordx2 v196, v[180:181], s[10:11] offset:3072
	s_nop 0
	v_mul_f32_e32 v76, v76, v210
	v_mul_f32_e32 v76, v12, v76
	v_fma_f32 v76, v156, v76, v172
	v_mul_f32_e32 v77, v77, v210
	v_mul_f32_e32 v77, v13, v77
	v_fma_f32 v77, v157, v77, v173
	v_mul_f32_e32 v78, v78, v210
	v_mul_f32_e32 v78, v14, v78
	v_fma_f32 v78, v158, v78, v174
	v_mul_f32_e32 v79, v79, v210
	v_mul_f32_e32 v79, v15, v79
	v_fma_f32 v79, v159, v79, v175
	v_cvt_pk_bf16_f32 v180, v76, v77
	v_cvt_pk_bf16_f32 v181, v78, v79
	global_store_dwordx2 v196, v[180:181], s[10:11] offset:3584
	s_nop 0
	s_add_u32 s14, s14, 0x1c0000
	s_addc_u32 s15, s15, 0
	global_load_dwordx4 v[48:51], v194, s[14:15]
	global_load_dwordx4 v[52:55], v194, s[14:15] offset:1024
	global_load_dwordx4 v[56:59], v194, s[14:15] offset:2048
	global_load_dwordx4 v[60:63], v194, s[14:15] offset:3072
	global_load_dwordx4 v[64:67], v195, s[14:15]
	global_load_dwordx4 v[68:71], v195, s[14:15] offset:1024
	global_load_dwordx4 v[72:75], v195, s[14:15] offset:2048
	global_load_dwordx4 v[76:79], v195, s[14:15] offset:3072
	s_waitcnt vmcnt(40)
	s_add_u32 s10, s10, 0xe0000
	s_addc_u32 s11, s11, 0
	v_pk_mul_f32 v[178:179], v[80:81], v[80:81]
	v_pk_fma_f32 v[178:179], v[82:83], v[82:83], v[178:179]
	v_pk_fma_f32 v[178:179], v[84:85], v[84:85], v[178:179]
	v_pk_fma_f32 v[178:179], v[86:87], v[86:87], v[178:179]
	v_pk_fma_f32 v[178:179], v[88:89], v[88:89], v[178:179]
	v_pk_fma_f32 v[178:179], v[90:91], v[90:91], v[178:179]
	v_pk_fma_f32 v[178:179], v[92:93], v[92:93], v[178:179]
	v_pk_fma_f32 v[178:179], v[94:95], v[94:95], v[178:179]
	v_pk_mul_f32 v[180:181], v[96:97], v[96:97]
	v_pk_fma_f32 v[180:181], v[98:99], v[98:99], v[180:181]
	v_pk_fma_f32 v[180:181], v[100:101], v[100:101], v[180:181]
	v_pk_fma_f32 v[180:181], v[102:103], v[102:103], v[180:181]
	v_pk_fma_f32 v[180:181], v[104:105], v[104:105], v[180:181]
	v_pk_fma_f32 v[180:181], v[106:107], v[106:107], v[180:181]
	v_pk_fma_f32 v[180:181], v[108:109], v[108:109], v[180:181]
	v_pk_fma_f32 v[180:181], v[110:111], v[110:111], v[180:181]
	v_add_f32_e32 v176, v178, v179
	v_add_f32_e32 v177, v180, v181
	ds_bpermute_b32 v178, v198, v176
	ds_bpermute_b32 v179, v198, v177
	s_waitcnt lgkmcnt(0)
	v_add_f32_e32 v176, v176, v178
	v_add_f32_e32 v177, v177, v179
	ds_bpermute_b32 v178, v199, v176
	ds_bpermute_b32 v179, v199, v177
	s_waitcnt lgkmcnt(0)
	v_add_f32_e32 v176, v176, v178
	v_add_f32_e32 v177, v177, v179
	ds_bpermute_b32 v178, v200, v176
	ds_bpermute_b32 v179, v200, v177
	s_waitcnt lgkmcnt(0)
	v_add_f32_e32 v176, v176, v178
	v_add_f32_e32 v177, v177, v179
	ds_bpermute_b32 v178, v201, v176
	ds_bpermute_b32 v179, v201, v177
	s_waitcnt lgkmcnt(0)
	v_add_f32_e32 v176, v176, v178
	v_add_f32_e32 v177, v177, v179
	ds_bpermute_b32 v178, v202, v176
	ds_bpermute_b32 v179, v202, v177
	s_waitcnt lgkmcnt(0)
	v_add_f32_e32 v176, v176, v178
	v_add_f32_e32 v177, v177, v179
	ds_bpermute_b32 v178, v203, v176
	ds_bpermute_b32 v179, v203, v177
	s_waitcnt lgkmcnt(0)
	v_add_f32_e32 v176, v176, v178
	v_add_f32_e32 v177, v177, v179
	v_fmamk_f32 v176, v176, 0x3a800000, v208
	v_mul_f32_e32 v178, 0x4b800000, v176
	v_cmp_gt_f32_e32 vcc, s27, v176
	s_nop 1
	v_cndmask_b32_e32 v176, v176, v178, vcc
	v_rsq_f32_e32 v209, v176
	s_nop 0
	v_mul_f32_e32 v178, 0x45800000, v209
	v_cndmask_b32_e32 v209, v209, v178, vcc
	v_fmamk_f32 v177, v177, 0x3a800000, v208
	v_mul_f32_e32 v178, 0x4b800000, v177
	v_cmp_gt_f32_e32 vcc, s27, v177
	s_nop 1
	v_cndmask_b32_e32 v177, v177, v178, vcc
	v_rsq_f32_e32 v210, v177
	s_nop 0
	v_mul_f32_e32 v178, 0x45800000, v210
	v_cndmask_b32_e32 v210, v210, v178, vcc
	v_mul_f32_e32 v80, v80, v209
	v_mul_f32_e32 v80, v0, v80
	v_fma_f32 v80, v144, v80, v160
	v_mul_f32_e32 v81, v81, v209
	v_mul_f32_e32 v81, v1, v81
	v_fma_f32 v81, v145, v81, v161
	v_mul_f32_e32 v82, v82, v209
	v_mul_f32_e32 v82, v2, v82
	v_fma_f32 v82, v146, v82, v162
	v_mul_f32_e32 v83, v83, v209
	v_mul_f32_e32 v83, v3, v83
	v_fma_f32 v83, v147, v83, v163
	v_cvt_pk_bf16_f32 v180, v80, v81
	v_cvt_pk_bf16_f32 v181, v82, v83
	global_store_dwordx2 v196, v[180:181], s[10:11]
	s_nop 0
	v_mul_f32_e32 v84, v84, v209
	v_mul_f32_e32 v84, v4, v84
	v_fma_f32 v84, v148, v84, v164
	v_mul_f32_e32 v85, v85, v209
	v_mul_f32_e32 v85, v5, v85
	v_fma_f32 v85, v149, v85, v165
	v_mul_f32_e32 v86, v86, v209
	v_mul_f32_e32 v86, v6, v86
	v_fma_f32 v86, v150, v86, v166
	v_mul_f32_e32 v87, v87, v209
	v_mul_f32_e32 v87, v7, v87
	v_fma_f32 v87, v151, v87, v167
	v_cvt_pk_bf16_f32 v180, v84, v85
	v_cvt_pk_bf16_f32 v181, v86, v87
	global_store_dwordx2 v196, v[180:181], s[10:11] offset:512
	s_nop 0
	v_mul_f32_e32 v88, v88, v209
	v_mul_f32_e32 v88, v8, v88
	v_fma_f32 v88, v152, v88, v168
	v_mul_f32_e32 v89, v89, v209
	v_mul_f32_e32 v89, v9, v89
	v_fma_f32 v89, v153, v89, v169
	v_mul_f32_e32 v90, v90, v209
	v_mul_f32_e32 v90, v10, v90
	v_fma_f32 v90, v154, v90, v170
	v_mul_f32_e32 v91, v91, v209
	v_mul_f32_e32 v91, v11, v91
	v_fma_f32 v91, v155, v91, v171
	v_cvt_pk_bf16_f32 v180, v88, v89
	v_cvt_pk_bf16_f32 v181, v90, v91
	global_store_dwordx2 v196, v[180:181], s[10:11] offset:1024
	s_nop 0
	v_mul_f32_e32 v92, v92, v209
	v_mul_f32_e32 v92, v12, v92
	v_fma_f32 v92, v156, v92, v172
	v_mul_f32_e32 v93, v93, v209
	v_mul_f32_e32 v93, v13, v93
	v_fma_f32 v93, v157, v93, v173
	v_mul_f32_e32 v94, v94, v209
	v_mul_f32_e32 v94, v14, v94
	v_fma_f32 v94, v158, v94, v174
	v_mul_f32_e32 v95, v95, v209
	v_mul_f32_e32 v95, v15, v95
	v_fma_f32 v95, v159, v95, v175
	v_cvt_pk_bf16_f32 v180, v92, v93
	v_cvt_pk_bf16_f32 v181, v94, v95
	global_store_dwordx2 v196, v[180:181], s[10:11] offset:1536
	s_nop 0
	v_mul_f32_e32 v96, v96, v210
	v_mul_f32_e32 v96, v0, v96
	v_fma_f32 v96, v144, v96, v160
	v_mul_f32_e32 v97, v97, v210
	v_mul_f32_e32 v97, v1, v97
	v_fma_f32 v97, v145, v97, v161
	v_mul_f32_e32 v98, v98, v210
	v_mul_f32_e32 v98, v2, v98
	v_fma_f32 v98, v146, v98, v162
	v_mul_f32_e32 v99, v99, v210
	v_mul_f32_e32 v99, v3, v99
	v_fma_f32 v99, v147, v99, v163
	v_cvt_pk_bf16_f32 v180, v96, v97
	v_cvt_pk_bf16_f32 v181, v98, v99
	global_store_dwordx2 v196, v[180:181], s[10:11] offset:2048
	s_nop 0
	v_mul_f32_e32 v100, v100, v210
	v_mul_f32_e32 v100, v4, v100
	v_fma_f32 v100, v148, v100, v164
	v_mul_f32_e32 v101, v101, v210
	v_mul_f32_e32 v101, v5, v101
	v_fma_f32 v101, v149, v101, v165
	v_mul_f32_e32 v102, v102, v210
	v_mul_f32_e32 v102, v6, v102
	v_fma_f32 v102, v150, v102, v166
	v_mul_f32_e32 v103, v103, v210
	v_mul_f32_e32 v103, v7, v103
	v_fma_f32 v103, v151, v103, v167
	v_cvt_pk_bf16_f32 v180, v100, v101
	v_cvt_pk_bf16_f32 v181, v102, v103
	global_store_dwordx2 v196, v[180:181], s[10:11] offset:2560
	s_nop 0
	v_mul_f32_e32 v104, v104, v210
	v_mul_f32_e32 v104, v8, v104
	v_fma_f32 v104, v152, v104, v168
	v_mul_f32_e32 v105, v105, v210
	v_mul_f32_e32 v105, v9, v105
	v_fma_f32 v105, v153, v105, v169
	v_mul_f32_e32 v106, v106, v210
	v_mul_f32_e32 v106, v10, v106
	v_fma_f32 v106, v154, v106, v170
	v_mul_f32_e32 v107, v107, v210
	v_mul_f32_e32 v107, v11, v107
	v_fma_f32 v107, v155, v107, v171
	v_cvt_pk_bf16_f32 v180, v104, v105
	v_cvt_pk_bf16_f32 v181, v106, v107
	global_store_dwordx2 v196, v[180:181], s[10:11] offset:3072
	s_nop 0
	v_mul_f32_e32 v108, v108, v210
	v_mul_f32_e32 v108, v12, v108
	v_fma_f32 v108, v156, v108, v172
	v_mul_f32_e32 v109, v109, v210
	v_mul_f32_e32 v109, v13, v109
	v_fma_f32 v109, v157, v109, v173
	v_mul_f32_e32 v110, v110, v210
	v_mul_f32_e32 v110, v14, v110
	v_fma_f32 v110, v158, v110, v174
	v_mul_f32_e32 v111, v111, v210
	v_mul_f32_e32 v111, v15, v111
	v_fma_f32 v111, v159, v111, v175
	v_cvt_pk_bf16_f32 v180, v108, v109
	v_cvt_pk_bf16_f32 v181, v110, v111
	global_store_dwordx2 v196, v[180:181], s[10:11] offset:3584
	s_nop 0
	s_add_u32 s14, s14, 0x1c0000
	s_addc_u32 s15, s15, 0
	global_load_dwordx4 v[80:83], v194, s[14:15]
	global_load_dwordx4 v[84:87], v194, s[14:15] offset:1024
	global_load_dwordx4 v[88:91], v194, s[14:15] offset:2048
	global_load_dwordx4 v[92:95], v194, s[14:15] offset:3072
	global_load_dwordx4 v[96:99], v195, s[14:15]
	global_load_dwordx4 v[100:103], v195, s[14:15] offset:1024
	global_load_dwordx4 v[104:107], v195, s[14:15] offset:2048
	global_load_dwordx4 v[108:111], v195, s[14:15] offset:3072
	s_waitcnt vmcnt(48)
	s_add_u32 s10, s10, 0xe0000
	s_addc_u32 s11, s11, 0
	v_pk_mul_f32 v[178:179], v[112:113], v[112:113]
	v_pk_fma_f32 v[178:179], v[114:115], v[114:115], v[178:179]
	v_pk_fma_f32 v[178:179], v[116:117], v[116:117], v[178:179]
	v_pk_fma_f32 v[178:179], v[118:119], v[118:119], v[178:179]
	v_pk_fma_f32 v[178:179], v[120:121], v[120:121], v[178:179]
	v_pk_fma_f32 v[178:179], v[122:123], v[122:123], v[178:179]
	v_pk_fma_f32 v[178:179], v[124:125], v[124:125], v[178:179]
	v_pk_fma_f32 v[178:179], v[126:127], v[126:127], v[178:179]
	v_pk_mul_f32 v[180:181], v[128:129], v[128:129]
	v_pk_fma_f32 v[180:181], v[130:131], v[130:131], v[180:181]
	v_pk_fma_f32 v[180:181], v[132:133], v[132:133], v[180:181]
	v_pk_fma_f32 v[180:181], v[134:135], v[134:135], v[180:181]
	v_pk_fma_f32 v[180:181], v[136:137], v[136:137], v[180:181]
	v_pk_fma_f32 v[180:181], v[138:139], v[138:139], v[180:181]
	v_pk_fma_f32 v[180:181], v[140:141], v[140:141], v[180:181]
	v_pk_fma_f32 v[180:181], v[142:143], v[142:143], v[180:181]
	v_add_f32_e32 v176, v178, v179
	v_add_f32_e32 v177, v180, v181
	ds_bpermute_b32 v178, v198, v176
	ds_bpermute_b32 v179, v198, v177
	s_waitcnt lgkmcnt(0)
	v_add_f32_e32 v176, v176, v178
	v_add_f32_e32 v177, v177, v179
	ds_bpermute_b32 v178, v199, v176
	ds_bpermute_b32 v179, v199, v177
	s_waitcnt lgkmcnt(0)
	v_add_f32_e32 v176, v176, v178
	v_add_f32_e32 v177, v177, v179
	ds_bpermute_b32 v178, v200, v176
	ds_bpermute_b32 v179, v200, v177
	s_waitcnt lgkmcnt(0)
	v_add_f32_e32 v176, v176, v178
	v_add_f32_e32 v177, v177, v179
	ds_bpermute_b32 v178, v201, v176
	ds_bpermute_b32 v179, v201, v177
	s_waitcnt lgkmcnt(0)
	v_add_f32_e32 v176, v176, v178
	v_add_f32_e32 v177, v177, v179
	ds_bpermute_b32 v178, v202, v176
	ds_bpermute_b32 v179, v202, v177
	s_waitcnt lgkmcnt(0)
	v_add_f32_e32 v176, v176, v178
	v_add_f32_e32 v177, v177, v179
	ds_bpermute_b32 v178, v203, v176
	ds_bpermute_b32 v179, v203, v177
	s_waitcnt lgkmcnt(0)
	v_add_f32_e32 v176, v176, v178
	v_add_f32_e32 v177, v177, v179
	v_fmamk_f32 v176, v176, 0x3a800000, v208
	v_mul_f32_e32 v178, 0x4b800000, v176
	v_cmp_gt_f32_e32 vcc, s27, v176
	s_nop 1
	v_cndmask_b32_e32 v176, v176, v178, vcc
	v_rsq_f32_e32 v209, v176
	s_nop 0
	v_mul_f32_e32 v178, 0x45800000, v209
	v_cndmask_b32_e32 v209, v209, v178, vcc
	v_fmamk_f32 v177, v177, 0x3a800000, v208
	v_mul_f32_e32 v178, 0x4b800000, v177
	v_cmp_gt_f32_e32 vcc, s27, v177
	s_nop 1
	v_cndmask_b32_e32 v177, v177, v178, vcc
	v_rsq_f32_e32 v210, v177
	s_nop 0
	v_mul_f32_e32 v178, 0x45800000, v210
	v_cndmask_b32_e32 v210, v210, v178, vcc
	v_mul_f32_e32 v112, v112, v209
	v_mul_f32_e32 v112, v0, v112
	v_fma_f32 v112, v144, v112, v160
	v_mul_f32_e32 v113, v113, v209
	v_mul_f32_e32 v113, v1, v113
	v_fma_f32 v113, v145, v113, v161
	v_mul_f32_e32 v114, v114, v209
	v_mul_f32_e32 v114, v2, v114
	v_fma_f32 v114, v146, v114, v162
	v_mul_f32_e32 v115, v115, v209
	v_mul_f32_e32 v115, v3, v115
	v_fma_f32 v115, v147, v115, v163
	v_cvt_pk_bf16_f32 v180, v112, v113
	v_cvt_pk_bf16_f32 v181, v114, v115
	global_store_dwordx2 v196, v[180:181], s[10:11]
	s_nop 0
	v_mul_f32_e32 v116, v116, v209
	v_mul_f32_e32 v116, v4, v116
	v_fma_f32 v116, v148, v116, v164
	v_mul_f32_e32 v117, v117, v209
	v_mul_f32_e32 v117, v5, v117
	v_fma_f32 v117, v149, v117, v165
	v_mul_f32_e32 v118, v118, v209
	v_mul_f32_e32 v118, v6, v118
	v_fma_f32 v118, v150, v118, v166
	v_mul_f32_e32 v119, v119, v209
	v_mul_f32_e32 v119, v7, v119
	v_fma_f32 v119, v151, v119, v167
	v_cvt_pk_bf16_f32 v180, v116, v117
	v_cvt_pk_bf16_f32 v181, v118, v119
	global_store_dwordx2 v196, v[180:181], s[10:11] offset:512
	s_nop 0
	v_mul_f32_e32 v120, v120, v209
	v_mul_f32_e32 v120, v8, v120
	v_fma_f32 v120, v152, v120, v168
	v_mul_f32_e32 v121, v121, v209
	v_mul_f32_e32 v121, v9, v121
	v_fma_f32 v121, v153, v121, v169
	v_mul_f32_e32 v122, v122, v209
	v_mul_f32_e32 v122, v10, v122
	v_fma_f32 v122, v154, v122, v170
	v_mul_f32_e32 v123, v123, v209
	v_mul_f32_e32 v123, v11, v123
	v_fma_f32 v123, v155, v123, v171
	v_cvt_pk_bf16_f32 v180, v120, v121
	v_cvt_pk_bf16_f32 v181, v122, v123
	global_store_dwordx2 v196, v[180:181], s[10:11] offset:1024
	s_nop 0
	v_mul_f32_e32 v124, v124, v209
	v_mul_f32_e32 v124, v12, v124
	v_fma_f32 v124, v156, v124, v172
	v_mul_f32_e32 v125, v125, v209
	v_mul_f32_e32 v125, v13, v125
	v_fma_f32 v125, v157, v125, v173
	v_mul_f32_e32 v126, v126, v209
	v_mul_f32_e32 v126, v14, v126
	v_fma_f32 v126, v158, v126, v174
	v_mul_f32_e32 v127, v127, v209
	v_mul_f32_e32 v127, v15, v127
	v_fma_f32 v127, v159, v127, v175
	v_cvt_pk_bf16_f32 v180, v124, v125
	v_cvt_pk_bf16_f32 v181, v126, v127
	global_store_dwordx2 v196, v[180:181], s[10:11] offset:1536
	s_nop 0
	v_mul_f32_e32 v128, v128, v210
	v_mul_f32_e32 v128, v0, v128
	v_fma_f32 v128, v144, v128, v160
	v_mul_f32_e32 v129, v129, v210
	v_mul_f32_e32 v129, v1, v129
	v_fma_f32 v129, v145, v129, v161
	v_mul_f32_e32 v130, v130, v210
	v_mul_f32_e32 v130, v2, v130
	v_fma_f32 v130, v146, v130, v162
	v_mul_f32_e32 v131, v131, v210
	v_mul_f32_e32 v131, v3, v131
	v_fma_f32 v131, v147, v131, v163
	v_cvt_pk_bf16_f32 v180, v128, v129
	v_cvt_pk_bf16_f32 v181, v130, v131
	global_store_dwordx2 v196, v[180:181], s[10:11] offset:2048
	s_nop 0
	v_mul_f32_e32 v132, v132, v210
	v_mul_f32_e32 v132, v4, v132
	v_fma_f32 v132, v148, v132, v164
	v_mul_f32_e32 v133, v133, v210
	v_mul_f32_e32 v133, v5, v133
	v_fma_f32 v133, v149, v133, v165
	v_mul_f32_e32 v134, v134, v210
	v_mul_f32_e32 v134, v6, v134
	v_fma_f32 v134, v150, v134, v166
	v_mul_f32_e32 v135, v135, v210
	v_mul_f32_e32 v135, v7, v135
	v_fma_f32 v135, v151, v135, v167
	v_cvt_pk_bf16_f32 v180, v132, v133
	v_cvt_pk_bf16_f32 v181, v134, v135
	global_store_dwordx2 v196, v[180:181], s[10:11] offset:2560
	s_nop 0
	v_mul_f32_e32 v136, v136, v210
	v_mul_f32_e32 v136, v8, v136
	v_fma_f32 v136, v152, v136, v168
	v_mul_f32_e32 v137, v137, v210
	v_mul_f32_e32 v137, v9, v137
	v_fma_f32 v137, v153, v137, v169
	v_mul_f32_e32 v138, v138, v210
	v_mul_f32_e32 v138, v10, v138
	v_fma_f32 v138, v154, v138, v170
	v_mul_f32_e32 v139, v139, v210
	v_mul_f32_e32 v139, v11, v139
	v_fma_f32 v139, v155, v139, v171
	v_cvt_pk_bf16_f32 v180, v136, v137
	v_cvt_pk_bf16_f32 v181, v138, v139
	global_store_dwordx2 v196, v[180:181], s[10:11] offset:3072
	s_nop 0
	v_mul_f32_e32 v140, v140, v210
	v_mul_f32_e32 v140, v12, v140
	v_fma_f32 v140, v156, v140, v172
	v_mul_f32_e32 v141, v141, v210
	v_mul_f32_e32 v141, v13, v141
	v_fma_f32 v141, v157, v141, v173
	v_mul_f32_e32 v142, v142, v210
	v_mul_f32_e32 v142, v14, v142
	v_fma_f32 v142, v158, v142, v174
	v_mul_f32_e32 v143, v143, v210
	v_mul_f32_e32 v143, v15, v143
	v_fma_f32 v143, v159, v143, v175
	v_cvt_pk_bf16_f32 v180, v140, v141
	v_cvt_pk_bf16_f32 v181, v142, v143
	global_store_dwordx2 v196, v[180:181], s[10:11] offset:3584
	s_nop 0
	s_add_u32 s14, s14, 0x1c0000
	s_addc_u32 s15, s15, 0
	global_load_dwordx4 v[112:115], v194, s[14:15]
	global_load_dwordx4 v[116:119], v194, s[14:15] offset:1024
	global_load_dwordx4 v[120:123], v194, s[14:15] offset:2048
	global_load_dwordx4 v[124:127], v194, s[14:15] offset:3072
	global_load_dwordx4 v[128:131], v195, s[14:15]
	global_load_dwordx4 v[132:135], v195, s[14:15] offset:1024
	global_load_dwordx4 v[136:139], v195, s[14:15] offset:2048
	global_load_dwordx4 v[140:143], v195, s[14:15] offset:3072
	s_waitcnt vmcnt(48)
	s_add_u32 s10, s10, 0xe0000
	s_addc_u32 s11, s11, 0
	v_pk_mul_f32 v[178:179], v[16:17], v[16:17]
	v_pk_fma_f32 v[178:179], v[18:19], v[18:19], v[178:179]
	v_pk_fma_f32 v[178:179], v[20:21], v[20:21], v[178:179]
	v_pk_fma_f32 v[178:179], v[22:23], v[22:23], v[178:179]
	v_pk_fma_f32 v[178:179], v[24:25], v[24:25], v[178:179]
	v_pk_fma_f32 v[178:179], v[26:27], v[26:27], v[178:179]
	v_pk_fma_f32 v[178:179], v[28:29], v[28:29], v[178:179]
	v_pk_fma_f32 v[178:179], v[30:31], v[30:31], v[178:179]
	v_pk_mul_f32 v[180:181], v[32:33], v[32:33]
	v_pk_fma_f32 v[180:181], v[34:35], v[34:35], v[180:181]
	v_pk_fma_f32 v[180:181], v[36:37], v[36:37], v[180:181]
	v_pk_fma_f32 v[180:181], v[38:39], v[38:39], v[180:181]
	v_pk_fma_f32 v[180:181], v[40:41], v[40:41], v[180:181]
	v_pk_fma_f32 v[180:181], v[42:43], v[42:43], v[180:181]
	v_pk_fma_f32 v[180:181], v[44:45], v[44:45], v[180:181]
	v_pk_fma_f32 v[180:181], v[46:47], v[46:47], v[180:181]
	v_add_f32_e32 v176, v178, v179
	v_add_f32_e32 v177, v180, v181
	ds_bpermute_b32 v178, v198, v176
	ds_bpermute_b32 v179, v198, v177
	s_waitcnt lgkmcnt(0)
	v_add_f32_e32 v176, v176, v178
	v_add_f32_e32 v177, v177, v179
	ds_bpermute_b32 v178, v199, v176
	ds_bpermute_b32 v179, v199, v177
	s_waitcnt lgkmcnt(0)
	v_add_f32_e32 v176, v176, v178
	v_add_f32_e32 v177, v177, v179
	ds_bpermute_b32 v178, v200, v176
	ds_bpermute_b32 v179, v200, v177
	s_waitcnt lgkmcnt(0)
	v_add_f32_e32 v176, v176, v178
	v_add_f32_e32 v177, v177, v179
	ds_bpermute_b32 v178, v201, v176
	ds_bpermute_b32 v179, v201, v177
	s_waitcnt lgkmcnt(0)
	v_add_f32_e32 v176, v176, v178
	v_add_f32_e32 v177, v177, v179
	ds_bpermute_b32 v178, v202, v176
	ds_bpermute_b32 v179, v202, v177
	s_waitcnt lgkmcnt(0)
	v_add_f32_e32 v176, v176, v178
	v_add_f32_e32 v177, v177, v179
	ds_bpermute_b32 v178, v203, v176
	ds_bpermute_b32 v179, v203, v177
	s_waitcnt lgkmcnt(0)
	v_add_f32_e32 v176, v176, v178
	v_add_f32_e32 v177, v177, v179
	v_fmamk_f32 v176, v176, 0x3a800000, v208
	v_mul_f32_e32 v178, 0x4b800000, v176
	v_cmp_gt_f32_e32 vcc, s27, v176
	s_nop 1
	v_cndmask_b32_e32 v176, v176, v178, vcc
	v_rsq_f32_e32 v209, v176
	s_nop 0
	v_mul_f32_e32 v178, 0x45800000, v209
	v_cndmask_b32_e32 v209, v209, v178, vcc
	v_fmamk_f32 v177, v177, 0x3a800000, v208
	v_mul_f32_e32 v178, 0x4b800000, v177
	v_cmp_gt_f32_e32 vcc, s27, v177
	s_nop 1
	v_cndmask_b32_e32 v177, v177, v178, vcc
	v_rsq_f32_e32 v210, v177
	s_nop 0
	v_mul_f32_e32 v178, 0x45800000, v210
	v_cndmask_b32_e32 v210, v210, v178, vcc
	v_mul_f32_e32 v16, v16, v209
	v_mul_f32_e32 v16, v0, v16
	v_fma_f32 v16, v144, v16, v160
	v_mul_f32_e32 v17, v17, v209
	v_mul_f32_e32 v17, v1, v17
	v_fma_f32 v17, v145, v17, v161
	v_mul_f32_e32 v18, v18, v209
	v_mul_f32_e32 v18, v2, v18
	v_fma_f32 v18, v146, v18, v162
	v_mul_f32_e32 v19, v19, v209
	v_mul_f32_e32 v19, v3, v19
	v_fma_f32 v19, v147, v19, v163
	v_cvt_pk_bf16_f32 v180, v16, v17
	v_cvt_pk_bf16_f32 v181, v18, v19
	global_store_dwordx2 v196, v[180:181], s[10:11]
	s_nop 0
	v_mul_f32_e32 v20, v20, v209
	v_mul_f32_e32 v20, v4, v20
	v_fma_f32 v20, v148, v20, v164
	v_mul_f32_e32 v21, v21, v209
	v_mul_f32_e32 v21, v5, v21
	v_fma_f32 v21, v149, v21, v165
	v_mul_f32_e32 v22, v22, v209
	v_mul_f32_e32 v22, v6, v22
	v_fma_f32 v22, v150, v22, v166
	v_mul_f32_e32 v23, v23, v209
	v_mul_f32_e32 v23, v7, v23
	v_fma_f32 v23, v151, v23, v167
	v_cvt_pk_bf16_f32 v180, v20, v21
	v_cvt_pk_bf16_f32 v181, v22, v23
	global_store_dwordx2 v196, v[180:181], s[10:11] offset:512
	s_nop 0
	v_mul_f32_e32 v24, v24, v209
	v_mul_f32_e32 v24, v8, v24
	v_fma_f32 v24, v152, v24, v168
	v_mul_f32_e32 v25, v25, v209
	v_mul_f32_e32 v25, v9, v25
	v_fma_f32 v25, v153, v25, v169
	v_mul_f32_e32 v26, v26, v209
	v_mul_f32_e32 v26, v10, v26
	v_fma_f32 v26, v154, v26, v170
	v_mul_f32_e32 v27, v27, v209
	v_mul_f32_e32 v27, v11, v27
	v_fma_f32 v27, v155, v27, v171
	v_cvt_pk_bf16_f32 v180, v24, v25
	v_cvt_pk_bf16_f32 v181, v26, v27
	global_store_dwordx2 v196, v[180:181], s[10:11] offset:1024
	s_nop 0
	v_mul_f32_e32 v28, v28, v209
	v_mul_f32_e32 v28, v12, v28
	v_fma_f32 v28, v156, v28, v172
	v_mul_f32_e32 v29, v29, v209
	v_mul_f32_e32 v29, v13, v29
	v_fma_f32 v29, v157, v29, v173
	v_mul_f32_e32 v30, v30, v209
	v_mul_f32_e32 v30, v14, v30
	v_fma_f32 v30, v158, v30, v174
	v_mul_f32_e32 v31, v31, v209
	v_mul_f32_e32 v31, v15, v31
	v_fma_f32 v31, v159, v31, v175
	v_cvt_pk_bf16_f32 v180, v28, v29
	v_cvt_pk_bf16_f32 v181, v30, v31
	global_store_dwordx2 v196, v[180:181], s[10:11] offset:1536
	s_nop 0
	v_mul_f32_e32 v32, v32, v210
	v_mul_f32_e32 v32, v0, v32
	v_fma_f32 v32, v144, v32, v160
	v_mul_f32_e32 v33, v33, v210
	v_mul_f32_e32 v33, v1, v33
	v_fma_f32 v33, v145, v33, v161
	v_mul_f32_e32 v34, v34, v210
	v_mul_f32_e32 v34, v2, v34
	v_fma_f32 v34, v146, v34, v162
	v_mul_f32_e32 v35, v35, v210
	v_mul_f32_e32 v35, v3, v35
	v_fma_f32 v35, v147, v35, v163
	v_cvt_pk_bf16_f32 v180, v32, v33
	v_cvt_pk_bf16_f32 v181, v34, v35
	global_store_dwordx2 v196, v[180:181], s[10:11] offset:2048
	s_nop 0
	v_mul_f32_e32 v36, v36, v210
	v_mul_f32_e32 v36, v4, v36
	v_fma_f32 v36, v148, v36, v164
	v_mul_f32_e32 v37, v37, v210
	v_mul_f32_e32 v37, v5, v37
	v_fma_f32 v37, v149, v37, v165
	v_mul_f32_e32 v38, v38, v210
	v_mul_f32_e32 v38, v6, v38
	v_fma_f32 v38, v150, v38, v166
	v_mul_f32_e32 v39, v39, v210
	v_mul_f32_e32 v39, v7, v39
	v_fma_f32 v39, v151, v39, v167
	v_cvt_pk_bf16_f32 v180, v36, v37
	v_cvt_pk_bf16_f32 v181, v38, v39
	global_store_dwordx2 v196, v[180:181], s[10:11] offset:2560
	s_nop 0
	v_mul_f32_e32 v40, v40, v210
	v_mul_f32_e32 v40, v8, v40
	v_fma_f32 v40, v152, v40, v168
	v_mul_f32_e32 v41, v41, v210
	v_mul_f32_e32 v41, v9, v41
	v_fma_f32 v41, v153, v41, v169
	v_mul_f32_e32 v42, v42, v210
	v_mul_f32_e32 v42, v10, v42
	v_fma_f32 v42, v154, v42, v170
	v_mul_f32_e32 v43, v43, v210
	v_mul_f32_e32 v43, v11, v43
	v_fma_f32 v43, v155, v43, v171
	v_cvt_pk_bf16_f32 v180, v40, v41
	v_cvt_pk_bf16_f32 v181, v42, v43
	global_store_dwordx2 v196, v[180:181], s[10:11] offset:3072
	s_nop 0
	v_mul_f32_e32 v44, v44, v210
	v_mul_f32_e32 v44, v12, v44
	v_fma_f32 v44, v156, v44, v172
	v_mul_f32_e32 v45, v45, v210
	v_mul_f32_e32 v45, v13, v45
	v_fma_f32 v45, v157, v45, v173
	v_mul_f32_e32 v46, v46, v210
	v_mul_f32_e32 v46, v14, v46
	v_fma_f32 v46, v158, v46, v174
	v_mul_f32_e32 v47, v47, v210
	v_mul_f32_e32 v47, v15, v47
	v_fma_f32 v47, v159, v47, v175
	v_cvt_pk_bf16_f32 v180, v44, v45
	v_cvt_pk_bf16_f32 v181, v46, v47
	global_store_dwordx2 v196, v[180:181], s[10:11] offset:3584
	s_nop 0
	s_add_u32 s14, s14, 0x1c0000
	s_addc_u32 s15, s15, 0
	global_load_dwordx4 v[16:19], v194, s[14:15]
	global_load_dwordx4 v[20:23], v194, s[14:15] offset:1024
	global_load_dwordx4 v[24:27], v194, s[14:15] offset:2048
	global_load_dwordx4 v[28:31], v194, s[14:15] offset:3072
	global_load_dwordx4 v[32:35], v195, s[14:15]
	global_load_dwordx4 v[36:39], v195, s[14:15] offset:1024
	global_load_dwordx4 v[40:43], v195, s[14:15] offset:2048
	global_load_dwordx4 v[44:47], v195, s[14:15] offset:3072
	s_waitcnt vmcnt(48)
	s_add_u32 s10, s10, 0xe0000
	s_addc_u32 s11, s11, 0
	v_pk_mul_f32 v[178:179], v[48:49], v[48:49]
	v_pk_fma_f32 v[178:179], v[50:51], v[50:51], v[178:179]
	v_pk_fma_f32 v[178:179], v[52:53], v[52:53], v[178:179]
	v_pk_fma_f32 v[178:179], v[54:55], v[54:55], v[178:179]
	v_pk_fma_f32 v[178:179], v[56:57], v[56:57], v[178:179]
	v_pk_fma_f32 v[178:179], v[58:59], v[58:59], v[178:179]
	v_pk_fma_f32 v[178:179], v[60:61], v[60:61], v[178:179]
	v_pk_fma_f32 v[178:179], v[62:63], v[62:63], v[178:179]
	v_pk_mul_f32 v[180:181], v[64:65], v[64:65]
	v_pk_fma_f32 v[180:181], v[66:67], v[66:67], v[180:181]
	v_pk_fma_f32 v[180:181], v[68:69], v[68:69], v[180:181]
	v_pk_fma_f32 v[180:181], v[70:71], v[70:71], v[180:181]
	v_pk_fma_f32 v[180:181], v[72:73], v[72:73], v[180:181]
	v_pk_fma_f32 v[180:181], v[74:75], v[74:75], v[180:181]
	v_pk_fma_f32 v[180:181], v[76:77], v[76:77], v[180:181]
	v_pk_fma_f32 v[180:181], v[78:79], v[78:79], v[180:181]
	v_add_f32_e32 v176, v178, v179
	v_add_f32_e32 v177, v180, v181
	ds_bpermute_b32 v178, v198, v176
	ds_bpermute_b32 v179, v198, v177
	s_waitcnt lgkmcnt(0)
	v_add_f32_e32 v176, v176, v178
	v_add_f32_e32 v177, v177, v179
	ds_bpermute_b32 v178, v199, v176
	ds_bpermute_b32 v179, v199, v177
	s_waitcnt lgkmcnt(0)
	v_add_f32_e32 v176, v176, v178
	v_add_f32_e32 v177, v177, v179
	ds_bpermute_b32 v178, v200, v176
	ds_bpermute_b32 v179, v200, v177
	s_waitcnt lgkmcnt(0)
	v_add_f32_e32 v176, v176, v178
	v_add_f32_e32 v177, v177, v179
	ds_bpermute_b32 v178, v201, v176
	ds_bpermute_b32 v179, v201, v177
	s_waitcnt lgkmcnt(0)
	v_add_f32_e32 v176, v176, v178
	v_add_f32_e32 v177, v177, v179
	ds_bpermute_b32 v178, v202, v176
	ds_bpermute_b32 v179, v202, v177
	s_waitcnt lgkmcnt(0)
	v_add_f32_e32 v176, v176, v178
	v_add_f32_e32 v177, v177, v179
	ds_bpermute_b32 v178, v203, v176
	ds_bpermute_b32 v179, v203, v177
	s_waitcnt lgkmcnt(0)
	v_add_f32_e32 v176, v176, v178
	v_add_f32_e32 v177, v177, v179
	v_fmamk_f32 v176, v176, 0x3a800000, v208
	v_mul_f32_e32 v178, 0x4b800000, v176
	v_cmp_gt_f32_e32 vcc, s27, v176
	s_nop 1
	v_cndmask_b32_e32 v176, v176, v178, vcc
	v_rsq_f32_e32 v209, v176
	s_nop 0
	v_mul_f32_e32 v178, 0x45800000, v209
	v_cndmask_b32_e32 v209, v209, v178, vcc
	v_fmamk_f32 v177, v177, 0x3a800000, v208
	v_mul_f32_e32 v178, 0x4b800000, v177
	v_cmp_gt_f32_e32 vcc, s27, v177
	s_nop 1
	v_cndmask_b32_e32 v177, v177, v178, vcc
	v_rsq_f32_e32 v210, v177
	s_nop 0
	v_mul_f32_e32 v178, 0x45800000, v210
	v_cndmask_b32_e32 v210, v210, v178, vcc
	v_mul_f32_e32 v48, v48, v209
	v_mul_f32_e32 v48, v0, v48
	v_fma_f32 v48, v144, v48, v160
	v_mul_f32_e32 v49, v49, v209
	v_mul_f32_e32 v49, v1, v49
	v_fma_f32 v49, v145, v49, v161
	v_mul_f32_e32 v50, v50, v209
	v_mul_f32_e32 v50, v2, v50
	v_fma_f32 v50, v146, v50, v162
	v_mul_f32_e32 v51, v51, v209
	v_mul_f32_e32 v51, v3, v51
	v_fma_f32 v51, v147, v51, v163
	v_cvt_pk_bf16_f32 v180, v48, v49
	v_cvt_pk_bf16_f32 v181, v50, v51
	global_store_dwordx2 v196, v[180:181], s[10:11]
	s_nop 0
	v_mul_f32_e32 v52, v52, v209
	v_mul_f32_e32 v52, v4, v52
	v_fma_f32 v52, v148, v52, v164
	v_mul_f32_e32 v53, v53, v209
	v_mul_f32_e32 v53, v5, v53
	v_fma_f32 v53, v149, v53, v165
	v_mul_f32_e32 v54, v54, v209
	v_mul_f32_e32 v54, v6, v54
	v_fma_f32 v54, v150, v54, v166
	v_mul_f32_e32 v55, v55, v209
	v_mul_f32_e32 v55, v7, v55
	v_fma_f32 v55, v151, v55, v167
	v_cvt_pk_bf16_f32 v180, v52, v53
	v_cvt_pk_bf16_f32 v181, v54, v55
	global_store_dwordx2 v196, v[180:181], s[10:11] offset:512
	s_nop 0
	v_mul_f32_e32 v56, v56, v209
	v_mul_f32_e32 v56, v8, v56
	v_fma_f32 v56, v152, v56, v168
	v_mul_f32_e32 v57, v57, v209
	v_mul_f32_e32 v57, v9, v57
	v_fma_f32 v57, v153, v57, v169
	v_mul_f32_e32 v58, v58, v209
	v_mul_f32_e32 v58, v10, v58
	v_fma_f32 v58, v154, v58, v170
	v_mul_f32_e32 v59, v59, v209
	v_mul_f32_e32 v59, v11, v59
	v_fma_f32 v59, v155, v59, v171
	v_cvt_pk_bf16_f32 v180, v56, v57
	v_cvt_pk_bf16_f32 v181, v58, v59
	global_store_dwordx2 v196, v[180:181], s[10:11] offset:1024
	s_nop 0
	v_mul_f32_e32 v60, v60, v209
	v_mul_f32_e32 v60, v12, v60
	v_fma_f32 v60, v156, v60, v172
	v_mul_f32_e32 v61, v61, v209
	v_mul_f32_e32 v61, v13, v61
	v_fma_f32 v61, v157, v61, v173
	v_mul_f32_e32 v62, v62, v209
	v_mul_f32_e32 v62, v14, v62
	v_fma_f32 v62, v158, v62, v174
	v_mul_f32_e32 v63, v63, v209
	v_mul_f32_e32 v63, v15, v63
	v_fma_f32 v63, v159, v63, v175
	v_cvt_pk_bf16_f32 v180, v60, v61
	v_cvt_pk_bf16_f32 v181, v62, v63
	global_store_dwordx2 v196, v[180:181], s[10:11] offset:1536
	s_nop 0
	v_mul_f32_e32 v64, v64, v210
	v_mul_f32_e32 v64, v0, v64
	v_fma_f32 v64, v144, v64, v160
	v_mul_f32_e32 v65, v65, v210
	v_mul_f32_e32 v65, v1, v65
	v_fma_f32 v65, v145, v65, v161
	v_mul_f32_e32 v66, v66, v210
	v_mul_f32_e32 v66, v2, v66
	v_fma_f32 v66, v146, v66, v162
	v_mul_f32_e32 v67, v67, v210
	v_mul_f32_e32 v67, v3, v67
	v_fma_f32 v67, v147, v67, v163
	v_cvt_pk_bf16_f32 v180, v64, v65
	v_cvt_pk_bf16_f32 v181, v66, v67
	global_store_dwordx2 v196, v[180:181], s[10:11] offset:2048
	s_nop 0
	v_mul_f32_e32 v68, v68, v210
	v_mul_f32_e32 v68, v4, v68
	v_fma_f32 v68, v148, v68, v164
	v_mul_f32_e32 v69, v69, v210
	v_mul_f32_e32 v69, v5, v69
	v_fma_f32 v69, v149, v69, v165
	v_mul_f32_e32 v70, v70, v210
	v_mul_f32_e32 v70, v6, v70
	v_fma_f32 v70, v150, v70, v166
	v_mul_f32_e32 v71, v71, v210
	v_mul_f32_e32 v71, v7, v71
	v_fma_f32 v71, v151, v71, v167
	v_cvt_pk_bf16_f32 v180, v68, v69
	v_cvt_pk_bf16_f32 v181, v70, v71
	global_store_dwordx2 v196, v[180:181], s[10:11] offset:2560
	s_nop 0
	v_mul_f32_e32 v72, v72, v210
	v_mul_f32_e32 v72, v8, v72
	v_fma_f32 v72, v152, v72, v168
	v_mul_f32_e32 v73, v73, v210
	v_mul_f32_e32 v73, v9, v73
	v_fma_f32 v73, v153, v73, v169
	v_mul_f32_e32 v74, v74, v210
	v_mul_f32_e32 v74, v10, v74
	v_fma_f32 v74, v154, v74, v170
	v_mul_f32_e32 v75, v75, v210
	v_mul_f32_e32 v75, v11, v75
	v_fma_f32 v75, v155, v75, v171
	v_cvt_pk_bf16_f32 v180, v72, v73
	v_cvt_pk_bf16_f32 v181, v74, v75
	global_store_dwordx2 v196, v[180:181], s[10:11] offset:3072
	s_nop 0
	v_mul_f32_e32 v76, v76, v210
	v_mul_f32_e32 v76, v12, v76
	v_fma_f32 v76, v156, v76, v172
	v_mul_f32_e32 v77, v77, v210
	v_mul_f32_e32 v77, v13, v77
	v_fma_f32 v77, v157, v77, v173
	v_mul_f32_e32 v78, v78, v210
	v_mul_f32_e32 v78, v14, v78
	v_fma_f32 v78, v158, v78, v174
	v_mul_f32_e32 v79, v79, v210
	v_mul_f32_e32 v79, v15, v79
	v_fma_f32 v79, v159, v79, v175
	v_cvt_pk_bf16_f32 v180, v76, v77
	v_cvt_pk_bf16_f32 v181, v78, v79
	global_store_dwordx2 v196, v[180:181], s[10:11] offset:3584
	s_nop 0
	s_add_u32 s20, s14, 0x1c0000
	s_addc_u32 s21, s15, 0
	s_cmp_eq_u32 s26, 0
	s_cselect_b32 s14, s14, s20
	s_cselect_b32 s15, s15, s21
	global_load_dwordx4 v[48:51], v194, s[14:15]
	global_load_dwordx4 v[52:55], v194, s[14:15] offset:1024
	global_load_dwordx4 v[56:59], v194, s[14:15] offset:2048
	global_load_dwordx4 v[60:63], v194, s[14:15] offset:3072
	global_load_dwordx4 v[64:67], v195, s[14:15]
	global_load_dwordx4 v[68:71], v195, s[14:15] offset:1024
	global_load_dwordx4 v[72:75], v195, s[14:15] offset:2048
	global_load_dwordx4 v[76:79], v195, s[14:15] offset:3072
	s_waitcnt vmcnt(48)
	s_add_u32 s10, s10, 0xe0000
	s_addc_u32 s11, s11, 0
	v_pk_mul_f32 v[178:179], v[80:81], v[80:81]
	v_pk_fma_f32 v[178:179], v[82:83], v[82:83], v[178:179]
	v_pk_fma_f32 v[178:179], v[84:85], v[84:85], v[178:179]
	v_pk_fma_f32 v[178:179], v[86:87], v[86:87], v[178:179]
	v_pk_fma_f32 v[178:179], v[88:89], v[88:89], v[178:179]
	v_pk_fma_f32 v[178:179], v[90:91], v[90:91], v[178:179]
	v_pk_fma_f32 v[178:179], v[92:93], v[92:93], v[178:179]
	v_pk_fma_f32 v[178:179], v[94:95], v[94:95], v[178:179]
	v_pk_mul_f32 v[180:181], v[96:97], v[96:97]
	v_pk_fma_f32 v[180:181], v[98:99], v[98:99], v[180:181]
	v_pk_fma_f32 v[180:181], v[100:101], v[100:101], v[180:181]
	v_pk_fma_f32 v[180:181], v[102:103], v[102:103], v[180:181]
	v_pk_fma_f32 v[180:181], v[104:105], v[104:105], v[180:181]
	v_pk_fma_f32 v[180:181], v[106:107], v[106:107], v[180:181]
	v_pk_fma_f32 v[180:181], v[108:109], v[108:109], v[180:181]
	v_pk_fma_f32 v[180:181], v[110:111], v[110:111], v[180:181]
	v_add_f32_e32 v176, v178, v179
	v_add_f32_e32 v177, v180, v181
	ds_bpermute_b32 v178, v198, v176
	ds_bpermute_b32 v179, v198, v177
	s_waitcnt lgkmcnt(0)
	v_add_f32_e32 v176, v176, v178
	v_add_f32_e32 v177, v177, v179
	ds_bpermute_b32 v178, v199, v176
	ds_bpermute_b32 v179, v199, v177
	s_waitcnt lgkmcnt(0)
	v_add_f32_e32 v176, v176, v178
	v_add_f32_e32 v177, v177, v179
	ds_bpermute_b32 v178, v200, v176
	ds_bpermute_b32 v179, v200, v177
	s_waitcnt lgkmcnt(0)
	v_add_f32_e32 v176, v176, v178
	v_add_f32_e32 v177, v177, v179
	ds_bpermute_b32 v178, v201, v176
	ds_bpermute_b32 v179, v201, v177
	s_waitcnt lgkmcnt(0)
	v_add_f32_e32 v176, v176, v178
	v_add_f32_e32 v177, v177, v179
	ds_bpermute_b32 v178, v202, v176
	ds_bpermute_b32 v179, v202, v177
	s_waitcnt lgkmcnt(0)
	v_add_f32_e32 v176, v176, v178
	v_add_f32_e32 v177, v177, v179
	ds_bpermute_b32 v178, v203, v176
	ds_bpermute_b32 v179, v203, v177
	s_waitcnt lgkmcnt(0)
	v_add_f32_e32 v176, v176, v178
	v_add_f32_e32 v177, v177, v179
	v_fmamk_f32 v176, v176, 0x3a800000, v208
	v_mul_f32_e32 v178, 0x4b800000, v176
	v_cmp_gt_f32_e32 vcc, s27, v176
	s_nop 1
	v_cndmask_b32_e32 v176, v176, v178, vcc
	v_rsq_f32_e32 v209, v176
	s_nop 0
	v_mul_f32_e32 v178, 0x45800000, v209
	v_cndmask_b32_e32 v209, v209, v178, vcc
	v_fmamk_f32 v177, v177, 0x3a800000, v208
	v_mul_f32_e32 v178, 0x4b800000, v177
	v_cmp_gt_f32_e32 vcc, s27, v177
	s_nop 1
	v_cndmask_b32_e32 v177, v177, v178, vcc
	v_rsq_f32_e32 v210, v177
	s_nop 0
	v_mul_f32_e32 v178, 0x45800000, v210
	v_cndmask_b32_e32 v210, v210, v178, vcc
	v_mul_f32_e32 v80, v80, v209
	v_mul_f32_e32 v80, v0, v80
	v_fma_f32 v80, v144, v80, v160
	v_mul_f32_e32 v81, v81, v209
	v_mul_f32_e32 v81, v1, v81
	v_fma_f32 v81, v145, v81, v161
	v_mul_f32_e32 v82, v82, v209
	v_mul_f32_e32 v82, v2, v82
	v_fma_f32 v82, v146, v82, v162
	v_mul_f32_e32 v83, v83, v209
	v_mul_f32_e32 v83, v3, v83
	v_fma_f32 v83, v147, v83, v163
	v_cvt_pk_bf16_f32 v180, v80, v81
	v_cvt_pk_bf16_f32 v181, v82, v83
	global_store_dwordx2 v196, v[180:181], s[10:11]
	s_nop 0
	v_mul_f32_e32 v84, v84, v209
	v_mul_f32_e32 v84, v4, v84
	v_fma_f32 v84, v148, v84, v164
	v_mul_f32_e32 v85, v85, v209
	v_mul_f32_e32 v85, v5, v85
	v_fma_f32 v85, v149, v85, v165
	v_mul_f32_e32 v86, v86, v209
	v_mul_f32_e32 v86, v6, v86
	v_fma_f32 v86, v150, v86, v166
	v_mul_f32_e32 v87, v87, v209
	v_mul_f32_e32 v87, v7, v87
	v_fma_f32 v87, v151, v87, v167
	v_cvt_pk_bf16_f32 v180, v84, v85
	v_cvt_pk_bf16_f32 v181, v86, v87
	global_store_dwordx2 v196, v[180:181], s[10:11] offset:512
	s_nop 0
	v_mul_f32_e32 v88, v88, v209
	v_mul_f32_e32 v88, v8, v88
	v_fma_f32 v88, v152, v88, v168
	v_mul_f32_e32 v89, v89, v209
	v_mul_f32_e32 v89, v9, v89
	v_fma_f32 v89, v153, v89, v169
	v_mul_f32_e32 v90, v90, v209
	v_mul_f32_e32 v90, v10, v90
	v_fma_f32 v90, v154, v90, v170
	v_mul_f32_e32 v91, v91, v209
	v_mul_f32_e32 v91, v11, v91
	v_fma_f32 v91, v155, v91, v171
	v_cvt_pk_bf16_f32 v180, v88, v89
	v_cvt_pk_bf16_f32 v181, v90, v91
	global_store_dwordx2 v196, v[180:181], s[10:11] offset:1024
	s_nop 0
	v_mul_f32_e32 v92, v92, v209
	v_mul_f32_e32 v92, v12, v92
	v_fma_f32 v92, v156, v92, v172
	v_mul_f32_e32 v93, v93, v209
	v_mul_f32_e32 v93, v13, v93
	v_fma_f32 v93, v157, v93, v173
	v_mul_f32_e32 v94, v94, v209
	v_mul_f32_e32 v94, v14, v94
	v_fma_f32 v94, v158, v94, v174
	v_mul_f32_e32 v95, v95, v209
	v_mul_f32_e32 v95, v15, v95
	v_fma_f32 v95, v159, v95, v175
	v_cvt_pk_bf16_f32 v180, v92, v93
	v_cvt_pk_bf16_f32 v181, v94, v95
	global_store_dwordx2 v196, v[180:181], s[10:11] offset:1536
	s_nop 0
	v_mul_f32_e32 v96, v96, v210
	v_mul_f32_e32 v96, v0, v96
	v_fma_f32 v96, v144, v96, v160
	v_mul_f32_e32 v97, v97, v210
	v_mul_f32_e32 v97, v1, v97
	v_fma_f32 v97, v145, v97, v161
	v_mul_f32_e32 v98, v98, v210
	v_mul_f32_e32 v98, v2, v98
	v_fma_f32 v98, v146, v98, v162
	v_mul_f32_e32 v99, v99, v210
	v_mul_f32_e32 v99, v3, v99
	v_fma_f32 v99, v147, v99, v163
	v_cvt_pk_bf16_f32 v180, v96, v97
	v_cvt_pk_bf16_f32 v181, v98, v99
	global_store_dwordx2 v196, v[180:181], s[10:11] offset:2048
	s_nop 0
	v_mul_f32_e32 v100, v100, v210
	v_mul_f32_e32 v100, v4, v100
	v_fma_f32 v100, v148, v100, v164
	v_mul_f32_e32 v101, v101, v210
	v_mul_f32_e32 v101, v5, v101
	v_fma_f32 v101, v149, v101, v165
	v_mul_f32_e32 v102, v102, v210
	v_mul_f32_e32 v102, v6, v102
	v_fma_f32 v102, v150, v102, v166
	v_mul_f32_e32 v103, v103, v210
	v_mul_f32_e32 v103, v7, v103
	v_fma_f32 v103, v151, v103, v167
	v_cvt_pk_bf16_f32 v180, v100, v101
	v_cvt_pk_bf16_f32 v181, v102, v103
	global_store_dwordx2 v196, v[180:181], s[10:11] offset:2560
	s_nop 0
	v_mul_f32_e32 v104, v104, v210
	v_mul_f32_e32 v104, v8, v104
	v_fma_f32 v104, v152, v104, v168
	v_mul_f32_e32 v105, v105, v210
	v_mul_f32_e32 v105, v9, v105
	v_fma_f32 v105, v153, v105, v169
	v_mul_f32_e32 v106, v106, v210
	v_mul_f32_e32 v106, v10, v106
	v_fma_f32 v106, v154, v106, v170
	v_mul_f32_e32 v107, v107, v210
	v_mul_f32_e32 v107, v11, v107
	v_fma_f32 v107, v155, v107, v171
	v_cvt_pk_bf16_f32 v180, v104, v105
	v_cvt_pk_bf16_f32 v181, v106, v107
	global_store_dwordx2 v196, v[180:181], s[10:11] offset:3072
	s_nop 0
	v_mul_f32_e32 v108, v108, v210
	v_mul_f32_e32 v108, v12, v108
	v_fma_f32 v108, v156, v108, v172
	v_mul_f32_e32 v109, v109, v210
	v_mul_f32_e32 v109, v13, v109
	v_fma_f32 v109, v157, v109, v173
	v_mul_f32_e32 v110, v110, v210
	v_mul_f32_e32 v110, v14, v110
	v_fma_f32 v110, v158, v110, v174
	v_mul_f32_e32 v111, v111, v210
	v_mul_f32_e32 v111, v15, v111
	v_fma_f32 v111, v159, v111, v175
	v_cvt_pk_bf16_f32 v180, v108, v109
	v_cvt_pk_bf16_f32 v181, v110, v111
	global_store_dwordx2 v196, v[180:181], s[10:11] offset:3584
	s_nop 0
	s_waitcnt vmcnt(40)
	s_add_u32 s10, s10, 0xe0000
	s_addc_u32 s11, s11, 0
	v_pk_mul_f32 v[178:179], v[112:113], v[112:113]
	v_pk_fma_f32 v[178:179], v[114:115], v[114:115], v[178:179]
	v_pk_fma_f32 v[178:179], v[116:117], v[116:117], v[178:179]
	v_pk_fma_f32 v[178:179], v[118:119], v[118:119], v[178:179]
	v_pk_fma_f32 v[178:179], v[120:121], v[120:121], v[178:179]
	v_pk_fma_f32 v[178:179], v[122:123], v[122:123], v[178:179]
	v_pk_fma_f32 v[178:179], v[124:125], v[124:125], v[178:179]
	v_pk_fma_f32 v[178:179], v[126:127], v[126:127], v[178:179]
	v_pk_mul_f32 v[180:181], v[128:129], v[128:129]
	v_pk_fma_f32 v[180:181], v[130:131], v[130:131], v[180:181]
	v_pk_fma_f32 v[180:181], v[132:133], v[132:133], v[180:181]
	v_pk_fma_f32 v[180:181], v[134:135], v[134:135], v[180:181]
	v_pk_fma_f32 v[180:181], v[136:137], v[136:137], v[180:181]
	v_pk_fma_f32 v[180:181], v[138:139], v[138:139], v[180:181]
	v_pk_fma_f32 v[180:181], v[140:141], v[140:141], v[180:181]
	v_pk_fma_f32 v[180:181], v[142:143], v[142:143], v[180:181]
	v_add_f32_e32 v176, v178, v179
	v_add_f32_e32 v177, v180, v181
	ds_bpermute_b32 v178, v198, v176
	ds_bpermute_b32 v179, v198, v177
	s_waitcnt lgkmcnt(0)
	v_add_f32_e32 v176, v176, v178
	v_add_f32_e32 v177, v177, v179
	ds_bpermute_b32 v178, v199, v176
	ds_bpermute_b32 v179, v199, v177
	s_waitcnt lgkmcnt(0)
	v_add_f32_e32 v176, v176, v178
	v_add_f32_e32 v177, v177, v179
	ds_bpermute_b32 v178, v200, v176
	ds_bpermute_b32 v179, v200, v177
	s_waitcnt lgkmcnt(0)
	v_add_f32_e32 v176, v176, v178
	v_add_f32_e32 v177, v177, v179
	ds_bpermute_b32 v178, v201, v176
	ds_bpermute_b32 v179, v201, v177
	s_waitcnt lgkmcnt(0)
	v_add_f32_e32 v176, v176, v178
	v_add_f32_e32 v177, v177, v179
	ds_bpermute_b32 v178, v202, v176
	ds_bpermute_b32 v179, v202, v177
	s_waitcnt lgkmcnt(0)
	v_add_f32_e32 v176, v176, v178
	v_add_f32_e32 v177, v177, v179
	ds_bpermute_b32 v178, v203, v176
	ds_bpermute_b32 v179, v203, v177
	s_waitcnt lgkmcnt(0)
	v_add_f32_e32 v176, v176, v178
	v_add_f32_e32 v177, v177, v179
	v_fmamk_f32 v176, v176, 0x3a800000, v208
	v_mul_f32_e32 v178, 0x4b800000, v176
	v_cmp_gt_f32_e32 vcc, s27, v176
	s_nop 1
	v_cndmask_b32_e32 v176, v176, v178, vcc
	v_rsq_f32_e32 v209, v176
	s_nop 0
	v_mul_f32_e32 v178, 0x45800000, v209
	v_cndmask_b32_e32 v209, v209, v178, vcc
	v_fmamk_f32 v177, v177, 0x3a800000, v208
	v_mul_f32_e32 v178, 0x4b800000, v177
	v_cmp_gt_f32_e32 vcc, s27, v177
	s_nop 1
	v_cndmask_b32_e32 v177, v177, v178, vcc
	v_rsq_f32_e32 v210, v177
	s_nop 0
	v_mul_f32_e32 v178, 0x45800000, v210
	v_cndmask_b32_e32 v210, v210, v178, vcc
	v_mul_f32_e32 v112, v112, v209
	v_mul_f32_e32 v112, v0, v112
	v_fma_f32 v112, v144, v112, v160
	v_mul_f32_e32 v113, v113, v209
	v_mul_f32_e32 v113, v1, v113
	v_fma_f32 v113, v145, v113, v161
	v_mul_f32_e32 v114, v114, v209
	v_mul_f32_e32 v114, v2, v114
	v_fma_f32 v114, v146, v114, v162
	v_mul_f32_e32 v115, v115, v209
	v_mul_f32_e32 v115, v3, v115
	v_fma_f32 v115, v147, v115, v163
	v_cvt_pk_bf16_f32 v180, v112, v113
	v_cvt_pk_bf16_f32 v181, v114, v115
	global_store_dwordx2 v196, v[180:181], s[10:11]
	s_nop 0
	v_mul_f32_e32 v116, v116, v209
	v_mul_f32_e32 v116, v4, v116
	v_fma_f32 v116, v148, v116, v164
	v_mul_f32_e32 v117, v117, v209
	v_mul_f32_e32 v117, v5, v117
	v_fma_f32 v117, v149, v117, v165
	v_mul_f32_e32 v118, v118, v209
	v_mul_f32_e32 v118, v6, v118
	v_fma_f32 v118, v150, v118, v166
	v_mul_f32_e32 v119, v119, v209
	v_mul_f32_e32 v119, v7, v119
	v_fma_f32 v119, v151, v119, v167
	v_cvt_pk_bf16_f32 v180, v116, v117
	v_cvt_pk_bf16_f32 v181, v118, v119
	global_store_dwordx2 v196, v[180:181], s[10:11] offset:512
	s_nop 0
	v_mul_f32_e32 v120, v120, v209
	v_mul_f32_e32 v120, v8, v120
	v_fma_f32 v120, v152, v120, v168
	v_mul_f32_e32 v121, v121, v209
	v_mul_f32_e32 v121, v9, v121
	v_fma_f32 v121, v153, v121, v169
	v_mul_f32_e32 v122, v122, v209
	v_mul_f32_e32 v122, v10, v122
	v_fma_f32 v122, v154, v122, v170
	v_mul_f32_e32 v123, v123, v209
	v_mul_f32_e32 v123, v11, v123
	v_fma_f32 v123, v155, v123, v171
	v_cvt_pk_bf16_f32 v180, v120, v121
	v_cvt_pk_bf16_f32 v181, v122, v123
	global_store_dwordx2 v196, v[180:181], s[10:11] offset:1024
	s_nop 0
	v_mul_f32_e32 v124, v124, v209
	v_mul_f32_e32 v124, v12, v124
	v_fma_f32 v124, v156, v124, v172
	v_mul_f32_e32 v125, v125, v209
	v_mul_f32_e32 v125, v13, v125
	v_fma_f32 v125, v157, v125, v173
	v_mul_f32_e32 v126, v126, v209
	v_mul_f32_e32 v126, v14, v126
	v_fma_f32 v126, v158, v126, v174
	v_mul_f32_e32 v127, v127, v209
	v_mul_f32_e32 v127, v15, v127
	v_fma_f32 v127, v159, v127, v175
	v_cvt_pk_bf16_f32 v180, v124, v125
	v_cvt_pk_bf16_f32 v181, v126, v127
	global_store_dwordx2 v196, v[180:181], s[10:11] offset:1536
	s_nop 0
	v_mul_f32_e32 v128, v128, v210
	v_mul_f32_e32 v128, v0, v128
	v_fma_f32 v128, v144, v128, v160
	v_mul_f32_e32 v129, v129, v210
	v_mul_f32_e32 v129, v1, v129
	v_fma_f32 v129, v145, v129, v161
	v_mul_f32_e32 v130, v130, v210
	v_mul_f32_e32 v130, v2, v130
	v_fma_f32 v130, v146, v130, v162
	v_mul_f32_e32 v131, v131, v210
	v_mul_f32_e32 v131, v3, v131
	v_fma_f32 v131, v147, v131, v163
	v_cvt_pk_bf16_f32 v180, v128, v129
	v_cvt_pk_bf16_f32 v181, v130, v131
	global_store_dwordx2 v196, v[180:181], s[10:11] offset:2048
	s_nop 0
	v_mul_f32_e32 v132, v132, v210
	v_mul_f32_e32 v132, v4, v132
	v_fma_f32 v132, v148, v132, v164
	v_mul_f32_e32 v133, v133, v210
	v_mul_f32_e32 v133, v5, v133
	v_fma_f32 v133, v149, v133, v165
	v_mul_f32_e32 v134, v134, v210
	v_mul_f32_e32 v134, v6, v134
	v_fma_f32 v134, v150, v134, v166
	v_mul_f32_e32 v135, v135, v210
	v_mul_f32_e32 v135, v7, v135
	v_fma_f32 v135, v151, v135, v167
	v_cvt_pk_bf16_f32 v180, v132, v133
	v_cvt_pk_bf16_f32 v181, v134, v135
	global_store_dwordx2 v196, v[180:181], s[10:11] offset:2560
	s_nop 0
	v_mul_f32_e32 v136, v136, v210
	v_mul_f32_e32 v136, v8, v136
	v_fma_f32 v136, v152, v136, v168
	v_mul_f32_e32 v137, v137, v210
	v_mul_f32_e32 v137, v9, v137
	v_fma_f32 v137, v153, v137, v169
	v_mul_f32_e32 v138, v138, v210
	v_mul_f32_e32 v138, v10, v138
	v_fma_f32 v138, v154, v138, v170
	v_mul_f32_e32 v139, v139, v210
	v_mul_f32_e32 v139, v11, v139
	v_fma_f32 v139, v155, v139, v171
	v_cvt_pk_bf16_f32 v180, v136, v137
	v_cvt_pk_bf16_f32 v181, v138, v139
	global_store_dwordx2 v196, v[180:181], s[10:11] offset:3072
	s_nop 0
	v_mul_f32_e32 v140, v140, v210
	v_mul_f32_e32 v140, v12, v140
	v_fma_f32 v140, v156, v140, v172
	v_mul_f32_e32 v141, v141, v210
	v_mul_f32_e32 v141, v13, v141
	v_fma_f32 v141, v157, v141, v173
	v_mul_f32_e32 v142, v142, v210
	v_mul_f32_e32 v142, v14, v142
	v_fma_f32 v142, v158, v142, v174
	v_mul_f32_e32 v143, v143, v210
	v_mul_f32_e32 v143, v15, v143
	v_fma_f32 v143, v159, v143, v175
	v_cvt_pk_bf16_f32 v180, v140, v141
	v_cvt_pk_bf16_f32 v181, v142, v143
	global_store_dwordx2 v196, v[180:181], s[10:11] offset:3584
	s_nop 0
	s_waitcnt vmcnt(32)
	s_add_u32 s10, s10, 0xe0000
	s_addc_u32 s11, s11, 0
	v_pk_mul_f32 v[178:179], v[16:17], v[16:17]
	v_pk_fma_f32 v[178:179], v[18:19], v[18:19], v[178:179]
	v_pk_fma_f32 v[178:179], v[20:21], v[20:21], v[178:179]
	v_pk_fma_f32 v[178:179], v[22:23], v[22:23], v[178:179]
	v_pk_fma_f32 v[178:179], v[24:25], v[24:25], v[178:179]
	v_pk_fma_f32 v[178:179], v[26:27], v[26:27], v[178:179]
	v_pk_fma_f32 v[178:179], v[28:29], v[28:29], v[178:179]
	v_pk_fma_f32 v[178:179], v[30:31], v[30:31], v[178:179]
	v_pk_mul_f32 v[180:181], v[32:33], v[32:33]
	v_pk_fma_f32 v[180:181], v[34:35], v[34:35], v[180:181]
	v_pk_fma_f32 v[180:181], v[36:37], v[36:37], v[180:181]
	v_pk_fma_f32 v[180:181], v[38:39], v[38:39], v[180:181]
	v_pk_fma_f32 v[180:181], v[40:41], v[40:41], v[180:181]
	v_pk_fma_f32 v[180:181], v[42:43], v[42:43], v[180:181]
	v_pk_fma_f32 v[180:181], v[44:45], v[44:45], v[180:181]
	v_pk_fma_f32 v[180:181], v[46:47], v[46:47], v[180:181]
	v_add_f32_e32 v176, v178, v179
	v_add_f32_e32 v177, v180, v181
	ds_bpermute_b32 v178, v198, v176
	ds_bpermute_b32 v179, v198, v177
	s_waitcnt lgkmcnt(0)
	v_add_f32_e32 v176, v176, v178
	v_add_f32_e32 v177, v177, v179
	ds_bpermute_b32 v178, v199, v176
	ds_bpermute_b32 v179, v199, v177
	s_waitcnt lgkmcnt(0)
	v_add_f32_e32 v176, v176, v178
	v_add_f32_e32 v177, v177, v179
	ds_bpermute_b32 v178, v200, v176
	ds_bpermute_b32 v179, v200, v177
	s_waitcnt lgkmcnt(0)
	v_add_f32_e32 v176, v176, v178
	v_add_f32_e32 v177, v177, v179
	ds_bpermute_b32 v178, v201, v176
	ds_bpermute_b32 v179, v201, v177
	s_waitcnt lgkmcnt(0)
	v_add_f32_e32 v176, v176, v178
	v_add_f32_e32 v177, v177, v179
	ds_bpermute_b32 v178, v202, v176
	ds_bpermute_b32 v179, v202, v177
	s_waitcnt lgkmcnt(0)
	v_add_f32_e32 v176, v176, v178
	v_add_f32_e32 v177, v177, v179
	ds_bpermute_b32 v178, v203, v176
	ds_bpermute_b32 v179, v203, v177
	s_waitcnt lgkmcnt(0)
	v_add_f32_e32 v176, v176, v178
	v_add_f32_e32 v177, v177, v179
	v_fmamk_f32 v176, v176, 0x3a800000, v208
	v_mul_f32_e32 v178, 0x4b800000, v176
	v_cmp_gt_f32_e32 vcc, s27, v176
	s_nop 1
	v_cndmask_b32_e32 v176, v176, v178, vcc
	v_rsq_f32_e32 v209, v176
	s_nop 0
	v_mul_f32_e32 v178, 0x45800000, v209
	v_cndmask_b32_e32 v209, v209, v178, vcc
	v_fmamk_f32 v177, v177, 0x3a800000, v208
	v_mul_f32_e32 v178, 0x4b800000, v177
	v_cmp_gt_f32_e32 vcc, s27, v177
	s_nop 1
	v_cndmask_b32_e32 v177, v177, v178, vcc
	v_rsq_f32_e32 v210, v177
	s_nop 0
	v_mul_f32_e32 v178, 0x45800000, v210
	v_cndmask_b32_e32 v210, v210, v178, vcc
	v_mul_f32_e32 v16, v16, v209
	v_mul_f32_e32 v16, v0, v16
	v_fma_f32 v16, v144, v16, v160
	v_mul_f32_e32 v17, v17, v209
	v_mul_f32_e32 v17, v1, v17
	v_fma_f32 v17, v145, v17, v161
	v_mul_f32_e32 v18, v18, v209
	v_mul_f32_e32 v18, v2, v18
	v_fma_f32 v18, v146, v18, v162
	v_mul_f32_e32 v19, v19, v209
	v_mul_f32_e32 v19, v3, v19
	v_fma_f32 v19, v147, v19, v163
	v_cvt_pk_bf16_f32 v180, v16, v17
	v_cvt_pk_bf16_f32 v181, v18, v19
	global_store_dwordx2 v196, v[180:181], s[10:11]
	s_nop 0
	v_mul_f32_e32 v20, v20, v209
	v_mul_f32_e32 v20, v4, v20
	v_fma_f32 v20, v148, v20, v164
	v_mul_f32_e32 v21, v21, v209
	v_mul_f32_e32 v21, v5, v21
	v_fma_f32 v21, v149, v21, v165
	v_mul_f32_e32 v22, v22, v209
	v_mul_f32_e32 v22, v6, v22
	v_fma_f32 v22, v150, v22, v166
	v_mul_f32_e32 v23, v23, v209
	v_mul_f32_e32 v23, v7, v23
	v_fma_f32 v23, v151, v23, v167
	v_cvt_pk_bf16_f32 v180, v20, v21
	v_cvt_pk_bf16_f32 v181, v22, v23
	global_store_dwordx2 v196, v[180:181], s[10:11] offset:512
	s_nop 0
	v_mul_f32_e32 v24, v24, v209
	v_mul_f32_e32 v24, v8, v24
	v_fma_f32 v24, v152, v24, v168
	v_mul_f32_e32 v25, v25, v209
	v_mul_f32_e32 v25, v9, v25
	v_fma_f32 v25, v153, v25, v169
	v_mul_f32_e32 v26, v26, v209
	v_mul_f32_e32 v26, v10, v26
	v_fma_f32 v26, v154, v26, v170
	v_mul_f32_e32 v27, v27, v209
	v_mul_f32_e32 v27, v11, v27
	v_fma_f32 v27, v155, v27, v171
	v_cvt_pk_bf16_f32 v180, v24, v25
	v_cvt_pk_bf16_f32 v181, v26, v27
	global_store_dwordx2 v196, v[180:181], s[10:11] offset:1024
	s_nop 0
	v_mul_f32_e32 v28, v28, v209
	v_mul_f32_e32 v28, v12, v28
	v_fma_f32 v28, v156, v28, v172
	v_mul_f32_e32 v29, v29, v209
	v_mul_f32_e32 v29, v13, v29
	v_fma_f32 v29, v157, v29, v173
	v_mul_f32_e32 v30, v30, v209
	v_mul_f32_e32 v30, v14, v30
	v_fma_f32 v30, v158, v30, v174
	v_mul_f32_e32 v31, v31, v209
	v_mul_f32_e32 v31, v15, v31
	v_fma_f32 v31, v159, v31, v175
	v_cvt_pk_bf16_f32 v180, v28, v29
	v_cvt_pk_bf16_f32 v181, v30, v31
	global_store_dwordx2 v196, v[180:181], s[10:11] offset:1536
	s_nop 0
	v_mul_f32_e32 v32, v32, v210
	v_mul_f32_e32 v32, v0, v32
	v_fma_f32 v32, v144, v32, v160
	v_mul_f32_e32 v33, v33, v210
	v_mul_f32_e32 v33, v1, v33
	v_fma_f32 v33, v145, v33, v161
	v_mul_f32_e32 v34, v34, v210
	v_mul_f32_e32 v34, v2, v34
	v_fma_f32 v34, v146, v34, v162
	v_mul_f32_e32 v35, v35, v210
	v_mul_f32_e32 v35, v3, v35
	v_fma_f32 v35, v147, v35, v163
	v_cvt_pk_bf16_f32 v180, v32, v33
	v_cvt_pk_bf16_f32 v181, v34, v35
	global_store_dwordx2 v196, v[180:181], s[10:11] offset:2048
	s_nop 0
	v_mul_f32_e32 v36, v36, v210
	v_mul_f32_e32 v36, v4, v36
	v_fma_f32 v36, v148, v36, v164
	v_mul_f32_e32 v37, v37, v210
	v_mul_f32_e32 v37, v5, v37
	v_fma_f32 v37, v149, v37, v165
	v_mul_f32_e32 v38, v38, v210
	v_mul_f32_e32 v38, v6, v38
	v_fma_f32 v38, v150, v38, v166
	v_mul_f32_e32 v39, v39, v210
	v_mul_f32_e32 v39, v7, v39
	v_fma_f32 v39, v151, v39, v167
	v_cvt_pk_bf16_f32 v180, v36, v37
	v_cvt_pk_bf16_f32 v181, v38, v39
	global_store_dwordx2 v196, v[180:181], s[10:11] offset:2560
	s_nop 0
	v_mul_f32_e32 v40, v40, v210
	v_mul_f32_e32 v40, v8, v40
	v_fma_f32 v40, v152, v40, v168
	v_mul_f32_e32 v41, v41, v210
	v_mul_f32_e32 v41, v9, v41
	v_fma_f32 v41, v153, v41, v169
	v_mul_f32_e32 v42, v42, v210
	v_mul_f32_e32 v42, v10, v42
	v_fma_f32 v42, v154, v42, v170
	v_mul_f32_e32 v43, v43, v210
	v_mul_f32_e32 v43, v11, v43
	v_fma_f32 v43, v155, v43, v171
	v_cvt_pk_bf16_f32 v180, v40, v41
	v_cvt_pk_bf16_f32 v181, v42, v43
	global_store_dwordx2 v196, v[180:181], s[10:11] offset:3072
	s_nop 0
	v_mul_f32_e32 v44, v44, v210
	v_mul_f32_e32 v44, v12, v44
	v_fma_f32 v44, v156, v44, v172
	v_mul_f32_e32 v45, v45, v210
	v_mul_f32_e32 v45, v13, v45
	v_fma_f32 v45, v157, v45, v173
	v_mul_f32_e32 v46, v46, v210
	v_mul_f32_e32 v46, v14, v46
	v_fma_f32 v46, v158, v46, v174
	v_mul_f32_e32 v47, v47, v210
	v_mul_f32_e32 v47, v15, v47
	v_fma_f32 v47, v159, v47, v175
	v_cvt_pk_bf16_f32 v180, v44, v45
	v_cvt_pk_bf16_f32 v181, v46, v47
	global_store_dwordx2 v196, v[180:181], s[10:11] offset:3584
	s_nop 0
	s_cmp_eq_u32 s26, 0
	s_cbranch_scc1 .LBB0_179
	s_waitcnt vmcnt(24)
	s_add_u32 s10, s10, 0xe0000
	s_addc_u32 s11, s11, 0
	v_pk_mul_f32 v[178:179], v[48:49], v[48:49]
	v_pk_fma_f32 v[178:179], v[50:51], v[50:51], v[178:179]
	v_pk_fma_f32 v[178:179], v[52:53], v[52:53], v[178:179]
	v_pk_fma_f32 v[178:179], v[54:55], v[54:55], v[178:179]
	v_pk_fma_f32 v[178:179], v[56:57], v[56:57], v[178:179]
	v_pk_fma_f32 v[178:179], v[58:59], v[58:59], v[178:179]
	v_pk_fma_f32 v[178:179], v[60:61], v[60:61], v[178:179]
	v_pk_fma_f32 v[178:179], v[62:63], v[62:63], v[178:179]
	v_pk_mul_f32 v[180:181], v[64:65], v[64:65]
	v_pk_fma_f32 v[180:181], v[66:67], v[66:67], v[180:181]
	v_pk_fma_f32 v[180:181], v[68:69], v[68:69], v[180:181]
	v_pk_fma_f32 v[180:181], v[70:71], v[70:71], v[180:181]
	v_pk_fma_f32 v[180:181], v[72:73], v[72:73], v[180:181]
	v_pk_fma_f32 v[180:181], v[74:75], v[74:75], v[180:181]
	v_pk_fma_f32 v[180:181], v[76:77], v[76:77], v[180:181]
	v_pk_fma_f32 v[180:181], v[78:79], v[78:79], v[180:181]
	v_add_f32_e32 v176, v178, v179
	v_add_f32_e32 v177, v180, v181
	ds_bpermute_b32 v178, v198, v176
	ds_bpermute_b32 v179, v198, v177
	s_waitcnt lgkmcnt(0)
	v_add_f32_e32 v176, v176, v178
	v_add_f32_e32 v177, v177, v179
	ds_bpermute_b32 v178, v199, v176
	ds_bpermute_b32 v179, v199, v177
	s_waitcnt lgkmcnt(0)
	v_add_f32_e32 v176, v176, v178
	v_add_f32_e32 v177, v177, v179
	ds_bpermute_b32 v178, v200, v176
	ds_bpermute_b32 v179, v200, v177
	s_waitcnt lgkmcnt(0)
	v_add_f32_e32 v176, v176, v178
	v_add_f32_e32 v177, v177, v179
	ds_bpermute_b32 v178, v201, v176
	ds_bpermute_b32 v179, v201, v177
	s_waitcnt lgkmcnt(0)
	v_add_f32_e32 v176, v176, v178
	v_add_f32_e32 v177, v177, v179
	ds_bpermute_b32 v178, v202, v176
	ds_bpermute_b32 v179, v202, v177
	s_waitcnt lgkmcnt(0)
	v_add_f32_e32 v176, v176, v178
	v_add_f32_e32 v177, v177, v179
	ds_bpermute_b32 v178, v203, v176
	ds_bpermute_b32 v179, v203, v177
	s_waitcnt lgkmcnt(0)
	v_add_f32_e32 v176, v176, v178
	v_add_f32_e32 v177, v177, v179
	v_fmamk_f32 v176, v176, 0x3a800000, v208
	v_mul_f32_e32 v178, 0x4b800000, v176
	v_cmp_gt_f32_e32 vcc, s27, v176
	s_nop 1
	v_cndmask_b32_e32 v176, v176, v178, vcc
	v_rsq_f32_e32 v209, v176
	s_nop 0
	v_mul_f32_e32 v178, 0x45800000, v209
	v_cndmask_b32_e32 v209, v209, v178, vcc
	v_fmamk_f32 v177, v177, 0x3a800000, v208
	v_mul_f32_e32 v178, 0x4b800000, v177
	v_cmp_gt_f32_e32 vcc, s27, v177
	s_nop 1
	v_cndmask_b32_e32 v177, v177, v178, vcc
	v_rsq_f32_e32 v210, v177
	s_nop 0
	v_mul_f32_e32 v178, 0x45800000, v210
	v_cndmask_b32_e32 v210, v210, v178, vcc
	v_mul_f32_e32 v48, v48, v209
	v_mul_f32_e32 v48, v0, v48
	v_fma_f32 v48, v144, v48, v160
	v_mul_f32_e32 v49, v49, v209
	v_mul_f32_e32 v49, v1, v49
	v_fma_f32 v49, v145, v49, v161
	v_mul_f32_e32 v50, v50, v209
	v_mul_f32_e32 v50, v2, v50
	v_fma_f32 v50, v146, v50, v162
	v_mul_f32_e32 v51, v51, v209
	v_mul_f32_e32 v51, v3, v51
	v_fma_f32 v51, v147, v51, v163
	v_cvt_pk_bf16_f32 v180, v48, v49
	v_cvt_pk_bf16_f32 v181, v50, v51
	global_store_dwordx2 v196, v[180:181], s[10:11]
	s_nop 0
	v_mul_f32_e32 v52, v52, v209
	v_mul_f32_e32 v52, v4, v52
	v_fma_f32 v52, v148, v52, v164
	v_mul_f32_e32 v53, v53, v209
	v_mul_f32_e32 v53, v5, v53
	v_fma_f32 v53, v149, v53, v165
	v_mul_f32_e32 v54, v54, v209
	v_mul_f32_e32 v54, v6, v54
	v_fma_f32 v54, v150, v54, v166
	v_mul_f32_e32 v55, v55, v209
	v_mul_f32_e32 v55, v7, v55
	v_fma_f32 v55, v151, v55, v167
	v_cvt_pk_bf16_f32 v180, v52, v53
	v_cvt_pk_bf16_f32 v181, v54, v55
	global_store_dwordx2 v196, v[180:181], s[10:11] offset:512
	s_nop 0
	v_mul_f32_e32 v56, v56, v209
	v_mul_f32_e32 v56, v8, v56
	v_fma_f32 v56, v152, v56, v168
	v_mul_f32_e32 v57, v57, v209
	v_mul_f32_e32 v57, v9, v57
	v_fma_f32 v57, v153, v57, v169
	v_mul_f32_e32 v58, v58, v209
	v_mul_f32_e32 v58, v10, v58
	v_fma_f32 v58, v154, v58, v170
	v_mul_f32_e32 v59, v59, v209
	v_mul_f32_e32 v59, v11, v59
	v_fma_f32 v59, v155, v59, v171
	v_cvt_pk_bf16_f32 v180, v56, v57
	v_cvt_pk_bf16_f32 v181, v58, v59
	global_store_dwordx2 v196, v[180:181], s[10:11] offset:1024
	s_nop 0
	v_mul_f32_e32 v60, v60, v209
	v_mul_f32_e32 v60, v12, v60
	v_fma_f32 v60, v156, v60, v172
	v_mul_f32_e32 v61, v61, v209
	v_mul_f32_e32 v61, v13, v61
	v_fma_f32 v61, v157, v61, v173
	v_mul_f32_e32 v62, v62, v209
	v_mul_f32_e32 v62, v14, v62
	v_fma_f32 v62, v158, v62, v174
	v_mul_f32_e32 v63, v63, v209
	v_mul_f32_e32 v63, v15, v63
	v_fma_f32 v63, v159, v63, v175
	v_cvt_pk_bf16_f32 v180, v60, v61
	v_cvt_pk_bf16_f32 v181, v62, v63
	global_store_dwordx2 v196, v[180:181], s[10:11] offset:1536
	s_nop 0
	v_mul_f32_e32 v64, v64, v210
	v_mul_f32_e32 v64, v0, v64
	v_fma_f32 v64, v144, v64, v160
	v_mul_f32_e32 v65, v65, v210
	v_mul_f32_e32 v65, v1, v65
	v_fma_f32 v65, v145, v65, v161
	v_mul_f32_e32 v66, v66, v210
	v_mul_f32_e32 v66, v2, v66
	v_fma_f32 v66, v146, v66, v162
	v_mul_f32_e32 v67, v67, v210
	v_mul_f32_e32 v67, v3, v67
	v_fma_f32 v67, v147, v67, v163
	v_cvt_pk_bf16_f32 v180, v64, v65
	v_cvt_pk_bf16_f32 v181, v66, v67
	global_store_dwordx2 v196, v[180:181], s[10:11] offset:2048
	s_nop 0
	v_mul_f32_e32 v68, v68, v210
	v_mul_f32_e32 v68, v4, v68
	v_fma_f32 v68, v148, v68, v164
	v_mul_f32_e32 v69, v69, v210
	v_mul_f32_e32 v69, v5, v69
	v_fma_f32 v69, v149, v69, v165
	v_mul_f32_e32 v70, v70, v210
	v_mul_f32_e32 v70, v6, v70
	v_fma_f32 v70, v150, v70, v166
	v_mul_f32_e32 v71, v71, v210
	v_mul_f32_e32 v71, v7, v71
	v_fma_f32 v71, v151, v71, v167
	v_cvt_pk_bf16_f32 v180, v68, v69
	v_cvt_pk_bf16_f32 v181, v70, v71
	global_store_dwordx2 v196, v[180:181], s[10:11] offset:2560
	s_nop 0
	v_mul_f32_e32 v72, v72, v210
	v_mul_f32_e32 v72, v8, v72
	v_fma_f32 v72, v152, v72, v168
	v_mul_f32_e32 v73, v73, v210
	v_mul_f32_e32 v73, v9, v73
	v_fma_f32 v73, v153, v73, v169
	v_mul_f32_e32 v74, v74, v210
	v_mul_f32_e32 v74, v10, v74
	v_fma_f32 v74, v154, v74, v170
	v_mul_f32_e32 v75, v75, v210
	v_mul_f32_e32 v75, v11, v75
	v_fma_f32 v75, v155, v75, v171
	v_cvt_pk_bf16_f32 v180, v72, v73
	v_cvt_pk_bf16_f32 v181, v74, v75
	global_store_dwordx2 v196, v[180:181], s[10:11] offset:3072
	s_nop 0
	v_mul_f32_e32 v76, v76, v210
	v_mul_f32_e32 v76, v12, v76
	v_fma_f32 v76, v156, v76, v172
	v_mul_f32_e32 v77, v77, v210
	v_mul_f32_e32 v77, v13, v77
	v_fma_f32 v77, v157, v77, v173
	v_mul_f32_e32 v78, v78, v210
	v_mul_f32_e32 v78, v14, v78
	v_fma_f32 v78, v158, v78, v174
	v_mul_f32_e32 v79, v79, v210
	v_mul_f32_e32 v79, v15, v79
	v_fma_f32 v79, v159, v79, v175
	v_cvt_pk_bf16_f32 v180, v76, v77
	v_cvt_pk_bf16_f32 v181, v78, v79
	global_store_dwordx2 v196, v[180:181], s[10:11] offset:3584
	s_nop 0
	s_branch .LBB0_179

.LBB0_242:
	s_add_i32 s44, s67, -16
	s_cmp_lt_u32 s44, -4
	s_mov_b64 s[44:45], -1
	s_cbranch_scc1 .LBB0_244
	s_ashr_i32 s44, s46, 12
	s_mul_hi_i32 s45, s44, 0x1100
	s_mulk_i32 s44, 0x1100
	s_add_u32 s44, s44, 0x100
	s_addc_u32 s45, s45, 0
	v_and_b32_e32 v136, 0xfcf, v144
	s_lshl_b32 s46, s67, 4
	v_lshl_add_u64 v[146:147], s[44:45], 0, v[136:137]
	v_add_u32_e32 v143, s46, v151
	v_lshlrev_b64 v[164:165], 5, v[146:147]
	v_mul_lo_u32 v146, v143, s61
	v_mov_b32_e32 v147, v137
	v_lshl_add_u64 v[146:147], s[42:43], 0, v[146:147]
	v_lshl_add_u64 v[148:149], v[146:147], 0, v[164:165]
	v_mov_b32_e32 v143, v137
	v_lshl_add_u64 v[148:149], v[148:149], 0, v[142:143]
	v_add_u32_e32 v145, s46, v152
	v_cvt_pk_bf16_f32 v160, v124, v125
	v_cvt_pk_bf16_f32 v161, v126, v127
	v_cvt_pk_bf16_f32 v162, v120, v121
	v_cvt_pk_bf16_f32 v163, v122, v123
	global_store_dwordx4 v[148:149], v[160:163], off sc1
	v_mul_lo_u32 v148, v145, s61
	v_mov_b32_e32 v149, v137
	v_lshl_add_u64 v[148:149], s[42:43], 0, v[148:149]
	v_lshl_add_u64 v[164:165], v[148:149], 0, v[164:165]
	v_cvt_pk_bf16_f32 v160, v116, v117
	v_cvt_pk_bf16_f32 v161, v118, v119
	v_lshl_add_u64 v[164:165], v[164:165], 0, v[142:143]
	v_cvt_pk_bf16_f32 v162, v112, v113
	v_cvt_pk_bf16_f32 v163, v114, v115
	global_store_dwordx4 v[164:165], v[160:163], off sc1
	s_nop 1
	v_or_b32_e32 v160, 16, v136
	v_mov_b32_e32 v161, v137
	v_lshl_add_u64 v[160:161], s[44:45], 0, v[160:161]
	v_lshlrev_b64 v[164:165], 5, v[160:161]
	v_lshl_add_u64 v[166:167], v[146:147], 0, v[164:165]
	v_cvt_pk_bf16_f32 v160, v108, v109
	v_cvt_pk_bf16_f32 v161, v110, v111
	v_lshl_add_u64 v[166:167], v[166:167], 0, v[142:143]
	v_lshl_add_u64 v[164:165], v[148:149], 0, v[164:165]
	v_cvt_pk_bf16_f32 v162, v104, v105
	v_cvt_pk_bf16_f32 v163, v106, v107
	global_store_dwordx4 v[166:167], v[160:163], off sc1
	v_lshl_add_u64 v[164:165], v[164:165], 0, v[142:143]
	s_nop 0
	v_cvt_pk_bf16_f32 v160, v100, v101
	v_cvt_pk_bf16_f32 v161, v102, v103
	v_cvt_pk_bf16_f32 v162, v96, v97
	v_cvt_pk_bf16_f32 v163, v98, v99
	global_store_dwordx4 v[164:165], v[160:163], off sc1
	s_nop 1
	v_or_b32_e32 v160, 32, v136
	v_mov_b32_e32 v161, v137
	v_lshl_add_u64 v[160:161], s[44:45], 0, v[160:161]
	v_lshlrev_b64 v[164:165], 5, v[160:161]
	v_lshl_add_u64 v[166:167], v[146:147], 0, v[164:165]
	v_cvt_pk_bf16_f32 v160, v92, v93
	v_cvt_pk_bf16_f32 v161, v94, v95
	v_lshl_add_u64 v[166:167], v[166:167], 0, v[142:143]
	v_lshl_add_u64 v[164:165], v[148:149], 0, v[164:165]
	v_cvt_pk_bf16_f32 v162, v88, v89
	v_cvt_pk_bf16_f32 v163, v90, v91
	global_store_dwordx4 v[166:167], v[160:163], off sc1
	v_lshl_add_u64 v[164:165], v[164:165], 0, v[142:143]
	v_or_b32_e32 v136, 48, v136
	v_cvt_pk_bf16_f32 v160, v84, v85
	v_cvt_pk_bf16_f32 v161, v86, v87
	v_cvt_pk_bf16_f32 v162, v80, v81
	v_cvt_pk_bf16_f32 v163, v82, v83
	global_store_dwordx4 v[164:165], v[160:163], off sc1
	s_nop 1
	v_lshl_add_u64 v[160:161], s[44:45], 0, v[136:137]
	v_lshlrev_b64 v[164:165], 5, v[160:161]
	v_lshl_add_u64 v[166:167], v[146:147], 0, v[164:165]
	v_cvt_pk_bf16_f32 v160, v76, v77
	v_cvt_pk_bf16_f32 v161, v78, v79
	v_lshl_add_u64 v[166:167], v[166:167], 0, v[142:143]
	v_lshl_add_u64 v[164:165], v[148:149], 0, v[164:165]
	v_add_u32_e32 v136, 0x80, v144
	v_cvt_pk_bf16_f32 v162, v72, v73
	v_cvt_pk_bf16_f32 v163, v74, v75
	global_store_dwordx4 v[166:167], v[160:163], off sc1
	v_lshl_add_u64 v[164:165], v[164:165], 0, v[142:143]
	v_ashrrev_i32_e32 v145, 12, v136
	v_cvt_pk_bf16_f32 v160, v68, v69
	v_cvt_pk_bf16_f32 v161, v70, v71
	v_cvt_pk_bf16_f32 v162, v64, v65
	v_cvt_pk_bf16_f32 v163, v66, v67
	global_store_dwordx4 v[164:165], v[160:163], off sc1
	s_mov_b64 s[44:45], 0x100
	v_and_b32_e32 v136, 0xfcf, v136
	v_mul_hi_i32_i24_e32 v161, 0x1100, v145
	v_mul_i32_i24_e32 v160, 0x1100, v145
	v_lshl_add_u64 v[164:165], v[160:161], 0, s[44:45]
	v_lshl_add_u64 v[160:161], v[164:165], 0, v[136:137]
	v_lshlrev_b64 v[166:167], 5, v[160:161]
	v_lshl_add_u64 v[168:169], v[146:147], 0, v[166:167]
	v_cvt_pk_bf16_f32 v160, v60, v61
	v_cvt_pk_bf16_f32 v161, v62, v63
	v_lshl_add_u64 v[168:169], v[168:169], 0, v[142:143]
	v_lshl_add_u64 v[166:167], v[148:149], 0, v[166:167]
	v_add_u32_e32 v136, 0x90, v144
	v_cvt_pk_bf16_f32 v162, v56, v57
	v_cvt_pk_bf16_f32 v163, v58, v59
	global_store_dwordx4 v[168:169], v[160:163], off sc1
	v_lshl_add_u64 v[166:167], v[166:167], 0, v[142:143]
	v_and_b32_e32 v136, 0xfdf, v136
	v_cvt_pk_bf16_f32 v160, v52, v53
	v_cvt_pk_bf16_f32 v161, v54, v55
	v_cvt_pk_bf16_f32 v162, v48, v49
	v_cvt_pk_bf16_f32 v163, v50, v51
	global_store_dwordx4 v[166:167], v[160:163], off sc1
	s_mov_b64 s[44:45], 0
	s_nop 0
	v_lshl_add_u64 v[160:161], v[164:165], 0, v[136:137]
	v_lshlrev_b64 v[166:167], 5, v[160:161]
	v_lshl_add_u64 v[168:169], v[146:147], 0, v[166:167]
	v_cvt_pk_bf16_f32 v160, v44, v45
	v_cvt_pk_bf16_f32 v161, v46, v47
	v_lshl_add_u64 v[168:169], v[168:169], 0, v[142:143]
	v_lshl_add_u64 v[166:167], v[148:149], 0, v[166:167]
	v_add_u32_e32 v136, 0xa0, v144
	v_cvt_pk_bf16_f32 v162, v40, v41
	v_cvt_pk_bf16_f32 v163, v42, v43
	global_store_dwordx4 v[168:169], v[160:163], off sc1
	v_lshl_add_u64 v[166:167], v[166:167], 0, v[142:143]
	v_and_b32_e32 v136, 0xfef, v136
	v_cvt_pk_bf16_f32 v160, v36, v37
	v_cvt_pk_bf16_f32 v161, v38, v39
	v_cvt_pk_bf16_f32 v162, v32, v33
	v_cvt_pk_bf16_f32 v163, v34, v35
	global_store_dwordx4 v[166:167], v[160:163], off sc1
	s_nop 1
	v_lshl_add_u64 v[160:161], v[164:165], 0, v[136:137]
	v_lshlrev_b64 v[166:167], 5, v[160:161]
	v_lshl_add_u64 v[168:169], v[146:147], 0, v[166:167]
	v_cvt_pk_bf16_f32 v160, v28, v29
	v_cvt_pk_bf16_f32 v161, v30, v31
	v_lshl_add_u64 v[168:169], v[168:169], 0, v[142:143]
	v_lshl_add_u64 v[166:167], v[148:149], 0, v[166:167]
	v_add_u32_e32 v136, 0xb0, v144
	v_cvt_pk_bf16_f32 v162, v24, v25
	v_cvt_pk_bf16_f32 v163, v26, v27
	global_store_dwordx4 v[168:169], v[160:163], off sc1
	v_lshl_add_u64 v[166:167], v[166:167], 0, v[142:143]
	v_and_b32_e32 v136, 0xfff, v136
	v_cvt_pk_bf16_f32 v160, v20, v21
	v_cvt_pk_bf16_f32 v161, v22, v23
	v_cvt_pk_bf16_f32 v162, v16, v17
	v_cvt_pk_bf16_f32 v163, v18, v19
	global_store_dwordx4 v[166:167], v[160:163], off sc1
	s_nop 1
	v_lshl_add_u64 v[160:161], v[164:165], 0, v[136:137]
	v_lshlrev_b64 v[164:165], 5, v[160:161]
	v_lshl_add_u64 v[146:147], v[146:147], 0, v[164:165]
	v_lshl_add_u64 v[146:147], v[146:147], 0, v[142:143]
	v_cvt_pk_bf16_f32 v160, v12, v13
	v_cvt_pk_bf16_f32 v161, v14, v15
	v_cvt_pk_bf16_f32 v162, v8, v9
	v_cvt_pk_bf16_f32 v163, v10, v11
	global_store_dwordx4 v[146:147], v[160:163], off sc1
	v_lshl_add_u64 v[146:147], v[148:149], 0, v[164:165]
	v_lshl_add_u64 v[146:147], v[146:147], 0, v[142:143]
	v_cvt_pk_bf16_f32 v160, v4, v5
	v_cvt_pk_bf16_f32 v161, v6, v7
	v_cvt_pk_bf16_f32 v162, v0, v1
	v_cvt_pk_bf16_f32 v163, v2, v3
	global_store_dwordx4 v[146:147], v[160:163], off sc1
.LBB0_244:
	s_andn2_b64 vcc, exec, s[44:45]
	s_cbranch_vccnz .LBB0_246
	s_cmp_lt_u32 s67, 12
	s_cselect_b64 s[44:45], -1, 0
	s_and_b64 s[46:47], s[44:45], exec
	s_cselect_b32 s46, 0, 0x4000000
	s_add_u32 s46, s38, s46
	s_addc_u32 s47, s39, 0
	s_and_b64 s[44:45], s[44:45], exec
	s_cselect_b32 s44, -8, -16
	s_add_i32 s44, s44, s67
	v_lshl_or_b32 v146, s44, 8, v153
	v_ashrrev_i32_e32 v147, 31, v146
	v_ashrrev_i32_e32 v145, 31, v144
	v_mul_f32_e32 v161, 0xbfb8aa3b, v122
	v_mul_f32_e32 v162, 0xbfb8aa3b, v127
	v_mul_f32_e32 v163, 0xbfb8aa3b, v123
	v_lshl_add_u64 v[148:149], v[146:147], 1, s[46:47]
	v_mul_f32_e32 v136, 0xbfb8aa3b, v124
	v_lshlrev_b64 v[146:147], 11, v[144:145]
	v_mul_f32_e32 v143, 0xbfb8aa3b, v120
	v_mul_f32_e32 v145, 0xbfb8aa3b, v125
	v_mul_f32_e32 v159, 0xbfb8aa3b, v121
	v_mul_f32_e32 v160, 0xbfb8aa3b, v126
	v_exp_f32_e32 v161, v161
	v_exp_f32_e32 v162, v162
	v_exp_f32_e32 v163, v163
	v_exp_f32_e32 v136, v136
	v_exp_f32_e32 v143, v143
	v_exp_f32_e32 v145, v145
	v_exp_f32_e32 v159, v159
	v_exp_f32_e32 v160, v160
	v_add_f32_e32 v161, 1.0, v161
	v_add_f32_e32 v162, 1.0, v162
	v_add_f32_e32 v163, 1.0, v163
	v_add_f32_e32 v136, 1.0, v136
	v_add_f32_e32 v143, 1.0, v143
	v_add_f32_e32 v145, 1.0, v145
	v_add_f32_e32 v159, 1.0, v159
	v_add_f32_e32 v160, 1.0, v160
	v_rcp_f32_e32 v161, v161
	v_rcp_f32_e32 v162, v162
	v_rcp_f32_e32 v163, v163
	v_rcp_f32_e32 v136, v136
	v_rcp_f32_e32 v143, v143
	v_rcp_f32_e32 v145, v145
	v_rcp_f32_e32 v159, v159
	v_rcp_f32_e32 v160, v160
	v_mul_f32_e32 v165, v122, v161
	v_mul_f32_e32 v161, v127, v162
	v_mul_f32_e32 v163, v123, v163
	v_lshl_add_u64 v[146:147], v[148:149], 0, v[146:147]
	v_mul_f32_e32 v136, v124, v136
	v_mul_f32_e32 v143, v120, v143
	v_mul_f32_e32 v145, v125, v145
	v_mul_f32_e32 v159, v121, v159
	v_mul_f32_e32 v164, v126, v160
	v_cvt_pk_bf16_f32 v160, v136, v145
	v_cvt_pk_bf16_f32 v161, v164, v161
	v_cvt_pk_bf16_f32 v162, v143, v159
	v_cvt_pk_bf16_f32 v163, v165, v163
	v_mul_f32_e32 v136, 0xbfb8aa3b, v116
	global_store_dwordx4 v[146:147], v[160:163], off sc1
	v_mul_f32_e32 v145, 0xbfb8aa3b, v117
	v_exp_f32_e32 v136, v136
	v_mul_f32_e32 v160, 0xbfb8aa3b, v118
	v_mul_f32_e32 v161, 0xbfb8aa3b, v114
	v_mul_f32_e32 v162, 0xbfb8aa3b, v119
	v_mul_f32_e32 v163, 0xbfb8aa3b, v115
	v_mul_f32_e32 v143, 0xbfb8aa3b, v112
	v_exp_f32_e32 v145, v145
	v_mul_f32_e32 v159, 0xbfb8aa3b, v113
	v_exp_f32_e32 v160, v160
	v_exp_f32_e32 v161, v161
	v_exp_f32_e32 v162, v162
	v_exp_f32_e32 v163, v163
	v_exp_f32_e32 v143, v143
	v_exp_f32_e32 v159, v159
	v_add_f32_e32 v136, 1.0, v136
	v_add_f32_e32 v145, 1.0, v145
	v_add_f32_e32 v160, 1.0, v160
	v_add_f32_e32 v161, 1.0, v161
	v_add_f32_e32 v162, 1.0, v162
	v_add_f32_e32 v163, 1.0, v163
	v_rcp_f32_e32 v136, v136
	v_add_f32_e32 v143, 1.0, v143
	v_rcp_f32_e32 v145, v145
	v_add_f32_e32 v159, 1.0, v159
	v_rcp_f32_e32 v160, v160
	v_rcp_f32_e32 v161, v161
	v_rcp_f32_e32 v162, v162
	v_rcp_f32_e32 v163, v163
	v_rcp_f32_e32 v143, v143
	v_rcp_f32_e32 v159, v159
	v_mul_f32_e32 v136, v116, v136
	v_mul_f32_e32 v145, v117, v145
	v_mul_f32_e32 v164, v118, v160
	v_mul_f32_e32 v165, v114, v161
	v_mul_f32_e32 v161, v119, v162
	v_mul_f32_e32 v163, v115, v163
	v_cvt_pk_bf16_f32 v160, v136, v145
	v_mul_f32_e32 v143, v112, v143
	v_mul_f32_e32 v159, v113, v159
	v_cvt_pk_bf16_f32 v161, v164, v161
	v_cvt_pk_bf16_f32 v162, v143, v159
	v_cvt_pk_bf16_f32 v163, v165, v163
	global_store_dwordx4 v[146:147], v[160:163], off offset:256 sc1
	v_mul_f32_e32 v136, 0xbfb8aa3b, v108
	v_mul_f32_e32 v143, 0xbfb8aa3b, v104
	v_or_b32_e32 v160, 16, v144
	v_ashrrev_i32_e32 v161, 31, v160
	v_lshlrev_b64 v[160:161], 11, v[160:161]
	v_lshl_add_u64 v[164:165], v[148:149], 0, v[160:161]
	v_mul_f32_e32 v161, 0xbfb8aa3b, v106
	v_mul_f32_e32 v162, 0xbfb8aa3b, v111
	v_mul_f32_e32 v163, 0xbfb8aa3b, v107
	v_mul_f32_e32 v145, 0xbfb8aa3b, v109
	v_mul_f32_e32 v159, 0xbfb8aa3b, v105
	v_mul_f32_e32 v160, 0xbfb8aa3b, v110
	v_exp_f32_e32 v161, v161
	v_exp_f32_e32 v162, v162
	v_exp_f32_e32 v163, v163
	v_exp_f32_e32 v136, v136
	v_exp_f32_e32 v143, v143
	v_exp_f32_e32 v145, v145
	v_exp_f32_e32 v159, v159
	v_exp_f32_e32 v160, v160
	v_add_f32_e32 v161, 1.0, v161
	v_add_f32_e32 v162, 1.0, v162
	v_add_f32_e32 v163, 1.0, v163
	v_add_f32_e32 v136, 1.0, v136
	v_add_f32_e32 v143, 1.0, v143
	v_add_f32_e32 v145, 1.0, v145
	v_add_f32_e32 v159, 1.0, v159
	v_add_f32_e32 v160, 1.0, v160
	v_rcp_f32_e32 v161, v161
	v_rcp_f32_e32 v162, v162
	v_rcp_f32_e32 v163, v163
	v_rcp_f32_e32 v136, v136
	v_rcp_f32_e32 v143, v143
	v_rcp_f32_e32 v145, v145
	v_rcp_f32_e32 v159, v159
	v_rcp_f32_e32 v160, v160
	v_mul_f32_e32 v167, v106, v161
	v_mul_f32_e32 v161, v111, v162
	v_mul_f32_e32 v163, v107, v163
	v_mul_f32_e32 v136, v108, v136
	v_mul_f32_e32 v143, v104, v143
	v_mul_f32_e32 v145, v109, v145
	v_mul_f32_e32 v159, v105, v159
	v_mul_f32_e32 v166, v110, v160
	v_cvt_pk_bf16_f32 v160, v136, v145
	v_cvt_pk_bf16_f32 v161, v166, v161
	v_cvt_pk_bf16_f32 v162, v143, v159
	v_cvt_pk_bf16_f32 v163, v167, v163
	v_mul_f32_e32 v136, 0xbfb8aa3b, v100
	global_store_dwordx4 v[164:165], v[160:163], off sc1
	v_mul_f32_e32 v145, 0xbfb8aa3b, v101
	v_exp_f32_e32 v136, v136
	v_mul_f32_e32 v160, 0xbfb8aa3b, v102
	v_mul_f32_e32 v161, 0xbfb8aa3b, v98
	v_mul_f32_e32 v162, 0xbfb8aa3b, v103
	v_mul_f32_e32 v163, 0xbfb8aa3b, v99
	v_mul_f32_e32 v143, 0xbfb8aa3b, v96
	v_exp_f32_e32 v145, v145
	v_mul_f32_e32 v159, 0xbfb8aa3b, v97
	v_exp_f32_e32 v160, v160
	v_exp_f32_e32 v161, v161
	v_exp_f32_e32 v162, v162
	v_exp_f32_e32 v163, v163
	v_exp_f32_e32 v143, v143
	v_exp_f32_e32 v159, v159
	v_add_f32_e32 v136, 1.0, v136
	v_add_f32_e32 v145, 1.0, v145
	v_add_f32_e32 v160, 1.0, v160
	v_add_f32_e32 v161, 1.0, v161
	v_add_f32_e32 v162, 1.0, v162
	v_add_f32_e32 v163, 1.0, v163
	v_rcp_f32_e32 v136, v136
	v_add_f32_e32 v143, 1.0, v143
	v_rcp_f32_e32 v145, v145
	v_add_f32_e32 v159, 1.0, v159
	v_rcp_f32_e32 v160, v160
	v_rcp_f32_e32 v161, v161
	v_rcp_f32_e32 v162, v162
	v_rcp_f32_e32 v163, v163
	v_rcp_f32_e32 v143, v143
	v_rcp_f32_e32 v159, v159
	v_mul_f32_e32 v136, v100, v136
	v_mul_f32_e32 v145, v101, v145
	v_mul_f32_e32 v166, v102, v160
	v_mul_f32_e32 v167, v98, v161
	v_mul_f32_e32 v161, v103, v162
	v_mul_f32_e32 v163, v99, v163
	v_cvt_pk_bf16_f32 v160, v136, v145
	v_mul_f32_e32 v143, v96, v143
	v_mul_f32_e32 v159, v97, v159
	v_cvt_pk_bf16_f32 v161, v166, v161
	v_cvt_pk_bf16_f32 v162, v143, v159
	v_cvt_pk_bf16_f32 v163, v167, v163
	global_store_dwordx4 v[164:165], v[160:163], off offset:256 sc1
	v_mul_f32_e32 v136, 0xbfb8aa3b, v92
	v_mul_f32_e32 v143, 0xbfb8aa3b, v88
	v_or_b32_e32 v160, 32, v144
	v_ashrrev_i32_e32 v161, 31, v160
	v_lshlrev_b64 v[160:161], 11, v[160:161]
	v_lshl_add_u64 v[164:165], v[148:149], 0, v[160:161]
	v_mul_f32_e32 v161, 0xbfb8aa3b, v90
	v_mul_f32_e32 v162, 0xbfb8aa3b, v95
	v_mul_f32_e32 v163, 0xbfb8aa3b, v91
	v_mul_f32_e32 v145, 0xbfb8aa3b, v93
	v_mul_f32_e32 v159, 0xbfb8aa3b, v89
	v_mul_f32_e32 v160, 0xbfb8aa3b, v94
	v_exp_f32_e32 v161, v161
	v_exp_f32_e32 v162, v162
	v_exp_f32_e32 v163, v163
	v_exp_f32_e32 v136, v136
	v_exp_f32_e32 v143, v143
	v_exp_f32_e32 v145, v145
	v_exp_f32_e32 v159, v159
	v_exp_f32_e32 v160, v160
	v_add_f32_e32 v161, 1.0, v161
	v_add_f32_e32 v162, 1.0, v162
	v_add_f32_e32 v163, 1.0, v163
	v_add_f32_e32 v136, 1.0, v136
	v_add_f32_e32 v143, 1.0, v143
	v_add_f32_e32 v145, 1.0, v145
	v_add_f32_e32 v159, 1.0, v159
	v_add_f32_e32 v160, 1.0, v160
	v_rcp_f32_e32 v161, v161
	v_rcp_f32_e32 v162, v162
	v_rcp_f32_e32 v163, v163
	v_rcp_f32_e32 v136, v136
	v_rcp_f32_e32 v143, v143
	v_rcp_f32_e32 v145, v145
	v_rcp_f32_e32 v159, v159
	v_rcp_f32_e32 v160, v160
	v_mul_f32_e32 v167, v90, v161
	v_mul_f32_e32 v161, v95, v162
	v_mul_f32_e32 v163, v91, v163
	v_mul_f32_e32 v136, v92, v136
	v_mul_f32_e32 v143, v88, v143
	v_mul_f32_e32 v145, v93, v145
	v_mul_f32_e32 v159, v89, v159
	v_mul_f32_e32 v166, v94, v160
	v_cvt_pk_bf16_f32 v160, v136, v145
	v_cvt_pk_bf16_f32 v161, v166, v161
	v_cvt_pk_bf16_f32 v162, v143, v159
	v_cvt_pk_bf16_f32 v163, v167, v163
	v_mul_f32_e32 v136, 0xbfb8aa3b, v84
	global_store_dwordx4 v[164:165], v[160:163], off sc1
	v_mul_f32_e32 v145, 0xbfb8aa3b, v85
	v_exp_f32_e32 v136, v136
	v_mul_f32_e32 v160, 0xbfb8aa3b, v86
	v_mul_f32_e32 v161, 0xbfb8aa3b, v82
	v_mul_f32_e32 v162, 0xbfb8aa3b, v87
	v_mul_f32_e32 v163, 0xbfb8aa3b, v83
	v_mul_f32_e32 v143, 0xbfb8aa3b, v80
	v_exp_f32_e32 v145, v145
	v_mul_f32_e32 v159, 0xbfb8aa3b, v81
	v_exp_f32_e32 v160, v160
	v_exp_f32_e32 v161, v161
	v_exp_f32_e32 v162, v162
	v_exp_f32_e32 v163, v163
	v_exp_f32_e32 v143, v143
	v_exp_f32_e32 v159, v159
	v_add_f32_e32 v136, 1.0, v136
	v_add_f32_e32 v145, 1.0, v145
	v_add_f32_e32 v160, 1.0, v160
	v_add_f32_e32 v161, 1.0, v161
	v_add_f32_e32 v162, 1.0, v162
	v_add_f32_e32 v163, 1.0, v163
	v_rcp_f32_e32 v136, v136
	v_add_f32_e32 v143, 1.0, v143
	v_rcp_f32_e32 v145, v145
	v_add_f32_e32 v159, 1.0, v159
	v_rcp_f32_e32 v160, v160
	v_rcp_f32_e32 v161, v161
	v_rcp_f32_e32 v162, v162
	v_rcp_f32_e32 v163, v163
	v_rcp_f32_e32 v143, v143
	v_rcp_f32_e32 v159, v159
	v_mul_f32_e32 v136, v84, v136
	v_mul_f32_e32 v145, v85, v145
	v_mul_f32_e32 v166, v86, v160
	v_mul_f32_e32 v167, v82, v161
	v_mul_f32_e32 v161, v87, v162
	v_mul_f32_e32 v163, v83, v163
	v_cvt_pk_bf16_f32 v160, v136, v145
	v_mul_f32_e32 v143, v80, v143
	v_mul_f32_e32 v159, v81, v159
	v_cvt_pk_bf16_f32 v161, v166, v161
	v_cvt_pk_bf16_f32 v162, v143, v159
	v_cvt_pk_bf16_f32 v163, v167, v163
	global_store_dwordx4 v[164:165], v[160:163], off offset:256 sc1
	v_mul_f32_e32 v143, 0xbfb8aa3b, v72
	v_mul_f32_e32 v159, 0xbfb8aa3b, v73
	v_or_b32_e32 v160, 48, v144
	v_ashrrev_i32_e32 v161, 31, v160
	v_lshlrev_b64 v[160:161], 11, v[160:161]
	v_lshl_add_u64 v[148:149], v[148:149], 0, v[160:161]
	v_mul_f32_e32 v161, 0xbfb8aa3b, v74
	v_mul_f32_e32 v162, 0xbfb8aa3b, v79
	v_mul_f32_e32 v160, 0xbfb8aa3b, v78
	v_exp_f32_e32 v161, v161
	v_exp_f32_e32 v162, v162
	v_mul_f32_e32 v163, 0xbfb8aa3b, v75
	v_mul_f32_e32 v136, 0xbfb8aa3b, v76
	v_exp_f32_e32 v143, v143
	v_mul_f32_e32 v145, 0xbfb8aa3b, v77
	v_exp_f32_e32 v159, v159
	v_exp_f32_e32 v160, v160
	v_exp_f32_e32 v163, v163
	v_exp_f32_e32 v136, v136
	v_exp_f32_e32 v145, v145
	v_add_f32_e32 v161, 1.0, v161
	v_add_f32_e32 v162, 1.0, v162
	v_add_f32_e32 v143, 1.0, v143
	v_add_f32_e32 v159, 1.0, v159
	v_add_f32_e32 v160, 1.0, v160
	v_rcp_f32_e32 v161, v161
	v_rcp_f32_e32 v162, v162
	v_add_f32_e32 v163, 1.0, v163
	v_add_f32_e32 v136, 1.0, v136
	v_rcp_f32_e32 v143, v143
	v_add_f32_e32 v145, 1.0, v145
	v_rcp_f32_e32 v159, v159
	v_rcp_f32_e32 v160, v160
	v_rcp_f32_e32 v163, v163
	v_rcp_f32_e32 v136, v136
	v_rcp_f32_e32 v145, v145
	v_mul_f32_e32 v165, v74, v161
	v_mul_f32_e32 v161, v79, v162
	v_mul_f32_e32 v143, v72, v143
	v_mul_f32_e32 v159, v73, v159
	v_mul_f32_e32 v164, v78, v160
	v_mul_f32_e32 v163, v75, v163
	v_cvt_pk_bf16_f32 v161, v164, v161
	v_cvt_pk_bf16_f32 v162, v143, v159
	v_mul_f32_e32 v136, v76, v136
	v_mul_f32_e32 v145, v77, v145
	v_cvt_pk_bf16_f32 v160, v136, v145
	v_cvt_pk_bf16_f32 v163, v165, v163
	global_store_dwordx4 v[148:149], v[160:163], off sc1
	v_mul_f32_e32 v136, 0xbfb8aa3b, v68
	v_mul_f32_e32 v143, 0xbfb8aa3b, v64
	v_mul_f32_e32 v161, 0xbfb8aa3b, v66
	v_mul_f32_e32 v162, 0xbfb8aa3b, v71
	v_mul_f32_e32 v145, 0xbfb8aa3b, v69
	v_mul_f32_e32 v159, 0xbfb8aa3b, v65
	v_mul_f32_e32 v160, 0xbfb8aa3b, v70
	v_exp_f32_e32 v161, v161
	v_exp_f32_e32 v162, v162
	v_mul_f32_e32 v163, 0xbfb8aa3b, v67
	v_exp_f32_e32 v136, v136
	v_exp_f32_e32 v143, v143
	v_exp_f32_e32 v145, v145
	v_exp_f32_e32 v159, v159
	v_exp_f32_e32 v160, v160
	v_exp_f32_e32 v163, v163
	v_add_f32_e32 v161, 1.0, v161
	v_add_f32_e32 v162, 1.0, v162
	v_add_f32_e32 v136, 1.0, v136
	v_add_f32_e32 v143, 1.0, v143
	v_add_f32_e32 v145, 1.0, v145
	v_add_f32_e32 v159, 1.0, v159
	v_add_f32_e32 v160, 1.0, v160
	v_rcp_f32_e32 v161, v161
	v_rcp_f32_e32 v162, v162
	v_add_f32_e32 v163, 1.0, v163
	v_rcp_f32_e32 v136, v136
	v_rcp_f32_e32 v143, v143
	v_rcp_f32_e32 v145, v145
	v_rcp_f32_e32 v159, v159
	v_rcp_f32_e32 v160, v160
	v_rcp_f32_e32 v163, v163
	v_mul_f32_e32 v165, v66, v161
	v_mul_f32_e32 v161, v71, v162
	v_mul_f32_e32 v136, v68, v136
	v_mul_f32_e32 v143, v64, v143
	v_mul_f32_e32 v145, v69, v145
	v_mul_f32_e32 v159, v65, v159
	v_mul_f32_e32 v164, v70, v160
	v_mul_f32_e32 v163, v67, v163
	v_cvt_pk_bf16_f32 v160, v136, v145
	v_cvt_pk_bf16_f32 v161, v164, v161
	v_cvt_pk_bf16_f32 v162, v143, v159
	v_cvt_pk_bf16_f32 v163, v165, v163
	global_store_dwordx4 v[148:149], v[160:163], off offset:256 sc1
	v_mul_f32_e32 v143, 0xbfb8aa3b, v56
	v_mul_f32_e32 v159, 0xbfb8aa3b, v57
	v_mul_f32_e32 v160, 0xbfb8aa3b, v62
	v_mul_f32_e32 v161, 0xbfb8aa3b, v58
	v_mul_f32_e32 v162, 0xbfb8aa3b, v63
	v_exp_f32_e32 v160, v160
	v_exp_f32_e32 v161, v161
	v_exp_f32_e32 v162, v162
	v_mul_f32_e32 v163, 0xbfb8aa3b, v59
	v_exp_f32_e32 v163, v163
	v_mul_f32_e32 v136, 0xbfb8aa3b, v60
	v_exp_f32_e32 v143, v143
	v_mul_f32_e32 v145, 0xbfb8aa3b, v61
	v_exp_f32_e32 v159, v159
	v_exp_f32_e32 v136, v136
	v_exp_f32_e32 v145, v145
	v_add_f32_e32 v160, 1.0, v160
	v_add_f32_e32 v161, 1.0, v161
	v_add_f32_e32 v162, 1.0, v162
	v_rcp_f32_e32 v160, v160
	v_rcp_f32_e32 v161, v161
	v_rcp_f32_e32 v162, v162
	v_add_f32_e32 v163, 1.0, v163
	v_add_f32_e32 v143, 1.0, v143
	v_add_f32_e32 v159, 1.0, v159
	v_rcp_f32_e32 v163, v163
	v_add_f32_e32 v136, 1.0, v136
	v_rcp_f32_e32 v143, v143
	v_add_f32_e32 v145, 1.0, v145
	v_rcp_f32_e32 v159, v159
	v_rcp_f32_e32 v136, v136
	v_rcp_f32_e32 v145, v145
	v_mul_f32_e32 v164, v62, v160
	v_mul_f32_e32 v165, v58, v161
	v_mul_f32_e32 v161, v63, v162
	v_mul_f32_e32 v163, v59, v163
	v_cvt_pk_bf16_f32 v161, v164, v161
	v_add_co_u32_e32 v164, vcc, s62, v146
	v_mul_f32_e32 v143, v56, v143
	v_mul_f32_e32 v159, v57, v159
	v_cvt_pk_bf16_f32 v162, v143, v159
	v_cvt_pk_bf16_f32 v163, v165, v163
	v_addc_co_u32_e32 v165, vcc, 0, v147, vcc
	v_mul_f32_e32 v136, v60, v136
	v_mul_f32_e32 v145, v61, v145
	v_cvt_pk_bf16_f32 v160, v136, v145
	global_store_dwordx4 v[164:165], v[160:163], off sc1
	v_mul_f32_e32 v136, 0xbfb8aa3b, v52
	v_mul_f32_e32 v143, 0xbfb8aa3b, v48
	v_mul_f32_e32 v161, 0xbfb8aa3b, v50
	v_mul_f32_e32 v162, 0xbfb8aa3b, v55
	v_mul_f32_e32 v145, 0xbfb8aa3b, v53
	v_mul_f32_e32 v159, 0xbfb8aa3b, v49
	v_mul_f32_e32 v160, 0xbfb8aa3b, v54
	v_exp_f32_e32 v161, v161
	v_exp_f32_e32 v162, v162
	v_mul_f32_e32 v163, 0xbfb8aa3b, v51
	v_exp_f32_e32 v136, v136
	v_exp_f32_e32 v143, v143
	v_exp_f32_e32 v145, v145
	v_exp_f32_e32 v159, v159
	v_exp_f32_e32 v160, v160
	v_exp_f32_e32 v163, v163
	v_add_f32_e32 v161, 1.0, v161
	v_add_f32_e32 v162, 1.0, v162
	v_add_f32_e32 v136, 1.0, v136
	v_add_f32_e32 v143, 1.0, v143
	v_add_f32_e32 v145, 1.0, v145
	v_add_f32_e32 v159, 1.0, v159
	v_add_f32_e32 v160, 1.0, v160
	v_rcp_f32_e32 v161, v161
	v_rcp_f32_e32 v162, v162
	v_add_f32_e32 v163, 1.0, v163
	v_rcp_f32_e32 v136, v136
	v_rcp_f32_e32 v143, v143
	v_rcp_f32_e32 v145, v145
	v_rcp_f32_e32 v159, v159
	v_rcp_f32_e32 v160, v160
	v_rcp_f32_e32 v163, v163
	s_mov_b64 s[44:45], 0x40000
	v_mul_f32_e32 v165, v50, v161
	v_mul_f32_e32 v161, v55, v162
	v_lshl_add_u64 v[148:149], v[146:147], 0, s[44:45]
	v_mul_f32_e32 v136, v52, v136
	v_mul_f32_e32 v143, v48, v143
	v_mul_f32_e32 v145, v53, v145
	v_mul_f32_e32 v159, v49, v159
	v_mul_f32_e32 v164, v54, v160
	v_mul_f32_e32 v163, v51, v163
	v_cvt_pk_bf16_f32 v160, v136, v145
	v_cvt_pk_bf16_f32 v161, v164, v161
	v_cvt_pk_bf16_f32 v162, v143, v159
	v_cvt_pk_bf16_f32 v163, v165, v163
	global_store_dwordx4 v[148:149], v[160:163], off offset:256 sc1
	v_mul_f32_e32 v143, 0xbfb8aa3b, v40
	v_mul_f32_e32 v159, 0xbfb8aa3b, v41
	v_mul_f32_e32 v160, 0xbfb8aa3b, v46
	v_mul_f32_e32 v161, 0xbfb8aa3b, v42
	v_mul_f32_e32 v162, 0xbfb8aa3b, v47
	v_exp_f32_e32 v160, v160
	v_exp_f32_e32 v161, v161
	v_exp_f32_e32 v162, v162
	v_mul_f32_e32 v163, 0xbfb8aa3b, v43
	v_exp_f32_e32 v163, v163
	v_mul_f32_e32 v136, 0xbfb8aa3b, v44
	v_exp_f32_e32 v143, v143
	v_mul_f32_e32 v145, 0xbfb8aa3b, v45
	v_exp_f32_e32 v159, v159
	v_exp_f32_e32 v136, v136
	v_exp_f32_e32 v145, v145
	v_add_f32_e32 v160, 1.0, v160
	v_add_f32_e32 v161, 1.0, v161
	v_add_f32_e32 v162, 1.0, v162
	v_rcp_f32_e32 v160, v160
	v_rcp_f32_e32 v161, v161
	v_rcp_f32_e32 v162, v162
	v_add_f32_e32 v163, 1.0, v163
	v_add_f32_e32 v143, 1.0, v143
	v_add_f32_e32 v159, 1.0, v159
	v_rcp_f32_e32 v163, v163
	v_add_f32_e32 v136, 1.0, v136
	v_rcp_f32_e32 v143, v143
	v_add_f32_e32 v145, 1.0, v145
	v_rcp_f32_e32 v159, v159
	v_rcp_f32_e32 v136, v136
	v_rcp_f32_e32 v145, v145
	v_mul_f32_e32 v164, v46, v160
	v_mul_f32_e32 v165, v42, v161
	v_mul_f32_e32 v161, v47, v162
	v_mul_f32_e32 v163, v43, v163
	v_cvt_pk_bf16_f32 v161, v164, v161
	v_add_co_u32_e32 v164, vcc, s63, v146
	v_mul_f32_e32 v143, v40, v143
	v_mul_f32_e32 v159, v41, v159
	v_cvt_pk_bf16_f32 v162, v143, v159
	v_cvt_pk_bf16_f32 v163, v165, v163
	v_addc_co_u32_e32 v165, vcc, 0, v147, vcc
	v_mul_f32_e32 v136, v44, v136
	v_mul_f32_e32 v145, v45, v145
	v_cvt_pk_bf16_f32 v160, v136, v145
	global_store_dwordx4 v[164:165], v[160:163], off sc1
	v_mul_f32_e32 v136, 0xbfb8aa3b, v36
	v_mul_f32_e32 v143, 0xbfb8aa3b, v32
	v_mul_f32_e32 v161, 0xbfb8aa3b, v34
	v_mul_f32_e32 v162, 0xbfb8aa3b, v39
	v_mul_f32_e32 v145, 0xbfb8aa3b, v37
	v_mul_f32_e32 v159, 0xbfb8aa3b, v33
	v_mul_f32_e32 v160, 0xbfb8aa3b, v38
	v_exp_f32_e32 v161, v161
	v_exp_f32_e32 v162, v162
	v_mul_f32_e32 v163, 0xbfb8aa3b, v35
	v_exp_f32_e32 v136, v136
	v_exp_f32_e32 v143, v143
	v_exp_f32_e32 v145, v145
	v_exp_f32_e32 v159, v159
	v_exp_f32_e32 v160, v160
	v_exp_f32_e32 v163, v163
	v_add_f32_e32 v161, 1.0, v161
	v_add_f32_e32 v162, 1.0, v162
	v_add_f32_e32 v136, 1.0, v136
	v_add_f32_e32 v143, 1.0, v143
	v_add_f32_e32 v145, 1.0, v145
	v_add_f32_e32 v159, 1.0, v159
	v_add_f32_e32 v160, 1.0, v160
	v_rcp_f32_e32 v161, v161
	v_rcp_f32_e32 v162, v162
	v_add_f32_e32 v163, 1.0, v163
	v_rcp_f32_e32 v136, v136
	v_rcp_f32_e32 v143, v143
	v_rcp_f32_e32 v145, v145
	v_rcp_f32_e32 v159, v159
	v_rcp_f32_e32 v160, v160
	v_rcp_f32_e32 v163, v163
	s_mov_b64 s[44:45], 0x48000
	v_mul_f32_e32 v165, v34, v161
	v_mul_f32_e32 v161, v39, v162
	v_lshl_add_u64 v[148:149], v[146:147], 0, s[44:45]
	v_mul_f32_e32 v136, v36, v136
	v_mul_f32_e32 v143, v32, v143
	v_mul_f32_e32 v145, v37, v145
	v_mul_f32_e32 v159, v33, v159
	v_mul_f32_e32 v164, v38, v160
	v_mul_f32_e32 v163, v35, v163
	v_cvt_pk_bf16_f32 v160, v136, v145
	v_cvt_pk_bf16_f32 v161, v164, v161
	v_cvt_pk_bf16_f32 v162, v143, v159
	v_cvt_pk_bf16_f32 v163, v165, v163
	global_store_dwordx4 v[148:149], v[160:163], off offset:256 sc1
	v_mul_f32_e32 v143, 0xbfb8aa3b, v24
	v_mul_f32_e32 v159, 0xbfb8aa3b, v25
	v_mul_f32_e32 v160, 0xbfb8aa3b, v30
	v_mul_f32_e32 v161, 0xbfb8aa3b, v26
	v_mul_f32_e32 v162, 0xbfb8aa3b, v31
	v_exp_f32_e32 v160, v160
	v_exp_f32_e32 v161, v161
	v_exp_f32_e32 v162, v162
	v_mul_f32_e32 v163, 0xbfb8aa3b, v27
	v_exp_f32_e32 v163, v163
	v_mul_f32_e32 v136, 0xbfb8aa3b, v28
	v_exp_f32_e32 v143, v143
	v_mul_f32_e32 v145, 0xbfb8aa3b, v29
	v_exp_f32_e32 v159, v159
	v_exp_f32_e32 v136, v136
	v_exp_f32_e32 v145, v145
	v_add_f32_e32 v160, 1.0, v160
	v_add_f32_e32 v161, 1.0, v161
	v_add_f32_e32 v162, 1.0, v162
	v_rcp_f32_e32 v160, v160
	v_rcp_f32_e32 v161, v161
	v_rcp_f32_e32 v162, v162
	v_add_f32_e32 v163, 1.0, v163
	v_add_f32_e32 v143, 1.0, v143
	v_add_f32_e32 v159, 1.0, v159
	v_rcp_f32_e32 v163, v163
	v_add_f32_e32 v136, 1.0, v136
	v_rcp_f32_e32 v143, v143
	v_add_f32_e32 v145, 1.0, v145
	v_rcp_f32_e32 v159, v159
	v_rcp_f32_e32 v136, v136
	v_rcp_f32_e32 v145, v145
	v_mul_f32_e32 v164, v30, v160
	v_mul_f32_e32 v165, v26, v161
	v_mul_f32_e32 v161, v31, v162
	v_mul_f32_e32 v163, v27, v163
	v_cvt_pk_bf16_f32 v161, v164, v161
	v_add_co_u32_e32 v164, vcc, s64, v146
	v_mul_f32_e32 v143, v24, v143
	v_mul_f32_e32 v159, v25, v159
	v_cvt_pk_bf16_f32 v162, v143, v159
	v_cvt_pk_bf16_f32 v163, v165, v163
	v_addc_co_u32_e32 v165, vcc, 0, v147, vcc
	v_mul_f32_e32 v136, v28, v136
	v_mul_f32_e32 v145, v29, v145
	v_cvt_pk_bf16_f32 v160, v136, v145
	global_store_dwordx4 v[164:165], v[160:163], off sc1
	v_mul_f32_e32 v136, 0xbfb8aa3b, v20
	v_mul_f32_e32 v145, 0xbfb8aa3b, v21
	v_mul_f32_e32 v161, 0xbfb8aa3b, v18
	v_mul_f32_e32 v162, 0xbfb8aa3b, v23
	v_mul_f32_e32 v160, 0xbfb8aa3b, v22
	v_exp_f32_e32 v161, v161
	v_exp_f32_e32 v162, v162
	v_mul_f32_e32 v163, 0xbfb8aa3b, v19
	v_exp_f32_e32 v136, v136
	v_mul_f32_e32 v143, 0xbfb8aa3b, v16
	v_exp_f32_e32 v145, v145
	v_mul_f32_e32 v159, 0xbfb8aa3b, v17
	v_exp_f32_e32 v160, v160
	v_exp_f32_e32 v163, v163
	v_exp_f32_e32 v143, v143
	v_exp_f32_e32 v159, v159
	v_add_f32_e32 v161, 1.0, v161
	v_add_f32_e32 v162, 1.0, v162
	v_add_f32_e32 v136, 1.0, v136
	v_add_f32_e32 v145, 1.0, v145
	v_add_f32_e32 v160, 1.0, v160
	v_rcp_f32_e32 v161, v161
	v_rcp_f32_e32 v162, v162
	v_add_f32_e32 v163, 1.0, v163
	v_rcp_f32_e32 v136, v136
	v_add_f32_e32 v143, 1.0, v143
	v_rcp_f32_e32 v145, v145
	v_add_f32_e32 v159, 1.0, v159
	v_rcp_f32_e32 v160, v160
	v_rcp_f32_e32 v163, v163
	v_rcp_f32_e32 v143, v143
	v_rcp_f32_e32 v159, v159
	s_mov_b64 s[44:45], 0x50000
	v_mul_f32_e32 v165, v18, v161
	v_mul_f32_e32 v161, v23, v162
	v_lshl_add_u64 v[148:149], v[146:147], 0, s[44:45]
	v_mul_f32_e32 v136, v20, v136
	v_mul_f32_e32 v145, v21, v145
	v_mul_f32_e32 v164, v22, v160
	v_mul_f32_e32 v163, v19, v163
	v_cvt_pk_bf16_f32 v160, v136, v145
	v_cvt_pk_bf16_f32 v161, v164, v161
	v_mul_f32_e32 v143, v16, v143
	v_mul_f32_e32 v159, v17, v159
	v_cvt_pk_bf16_f32 v162, v143, v159
	v_cvt_pk_bf16_f32 v163, v165, v163
	global_store_dwordx4 v[148:149], v[160:163], off offset:256 sc1
	v_mul_f32_e32 v136, 0xbfb8aa3b, v12
	v_mul_f32_e32 v143, 0xbfb8aa3b, v8
	v_mul_f32_e32 v160, 0xbfb8aa3b, v15
	v_mul_f32_e32 v161, 0xbfb8aa3b, v11
	v_mul_f32_e32 v145, 0xbfb8aa3b, v13
	v_mul_f32_e32 v148, 0xbfb8aa3b, v9
	v_mul_f32_e32 v149, 0xbfb8aa3b, v14
	v_mul_f32_e32 v159, 0xbfb8aa3b, v10
	v_exp_f32_e32 v160, v160
	v_exp_f32_e32 v161, v161
	v_exp_f32_e32 v136, v136
	v_exp_f32_e32 v143, v143
	v_exp_f32_e32 v145, v145
	v_exp_f32_e32 v148, v148
	v_exp_f32_e32 v149, v149
	v_exp_f32_e32 v159, v159
	v_add_f32_e32 v160, 1.0, v160
	v_add_f32_e32 v161, 1.0, v161
	v_add_f32_e32 v136, 1.0, v136
	v_add_f32_e32 v143, 1.0, v143
	v_add_f32_e32 v145, 1.0, v145
	v_add_f32_e32 v148, 1.0, v148
	v_add_f32_e32 v149, 1.0, v149
	v_add_f32_e32 v159, 1.0, v159
	v_rcp_f32_e32 v160, v160
	v_rcp_f32_e32 v161, v161
	s_mov_b64 s[44:45], 0x58000
	v_rcp_f32_e32 v136, v136
	v_rcp_f32_e32 v143, v143
	v_rcp_f32_e32 v145, v145
	v_rcp_f32_e32 v148, v148
	v_rcp_f32_e32 v149, v149
	v_rcp_f32_e32 v159, v159
	v_lshl_add_u64 v[164:165], v[146:147], 0, s[44:45]
	s_mov_b32 s44, 0x58000
	v_add_co_u32_e32 v146, vcc, s44, v146
	v_mul_f32_e32 v162, v15, v160
	v_mul_f32_e32 v163, v11, v161
	v_addc_co_u32_e32 v147, vcc, 0, v147, vcc
	v_mul_f32_e32 v136, v12, v136
	v_mul_f32_e32 v143, v8, v143
	v_mul_f32_e32 v145, v13, v145
	v_mul_f32_e32 v148, v9, v148
	v_mul_f32_e32 v149, v14, v149
	v_mul_f32_e32 v159, v10, v159
	v_cvt_pk_bf16_f32 v160, v136, v145
	v_cvt_pk_bf16_f32 v161, v149, v162
	v_cvt_pk_bf16_f32 v162, v143, v148
	v_cvt_pk_bf16_f32 v163, v159, v163
	global_store_dwordx4 v[146:147], v[160:163], off sc1
	v_mul_f32_e32 v146, 0xbfb8aa3b, v1
	v_exp_f32_e32 v146, v146
	v_mul_f32_e32 v147, 0xbfb8aa3b, v6
	v_mul_f32_e32 v148, 0xbfb8aa3b, v2
	v_exp_f32_e32 v147, v147
	v_add_f32_e32 v146, 1.0, v146
	v_rcp_f32_e32 v146, v146
	v_exp_f32_e32 v148, v148
	v_mul_f32_e32 v136, 0xbfb8aa3b, v4
	v_mul_f32_e32 v143, 0xbfb8aa3b, v0
	v_mul_f32_e32 v149, v1, v146
	v_add_f32_e32 v146, 1.0, v147
	v_add_f32_e32 v147, 1.0, v148
	v_mul_f32_e32 v148, 0xbfb8aa3b, v7
	v_mul_f32_e32 v145, 0xbfb8aa3b, v5
	v_exp_f32_e32 v148, v148
	v_mul_f32_e32 v159, 0xbfb8aa3b, v3
	v_exp_f32_e32 v136, v136
	v_exp_f32_e32 v143, v143
	v_exp_f32_e32 v145, v145
	v_exp_f32_e32 v159, v159
	v_add_f32_e32 v148, 1.0, v148
	v_add_f32_e32 v136, 1.0, v136
	v_add_f32_e32 v143, 1.0, v143
	v_add_f32_e32 v145, 1.0, v145
	v_rcp_f32_e32 v147, v147
	v_rcp_f32_e32 v148, v148
	v_add_f32_e32 v159, 1.0, v159
	v_rcp_f32_e32 v136, v136
	v_rcp_f32_e32 v143, v143
	v_rcp_f32_e32 v145, v145
	v_rcp_f32_e32 v146, v146
	v_rcp_f32_e32 v159, v159
	v_mul_f32_e32 v161, v2, v147
	v_mul_f32_e32 v147, v7, v148
	v_mul_f32_e32 v136, v4, v136
	v_mul_f32_e32 v143, v0, v143
	v_mul_f32_e32 v145, v5, v145
	v_mul_f32_e32 v160, v6, v146
	v_mul_f32_e32 v159, v3, v159
	v_cvt_pk_bf16_f32 v146, v136, v145
	v_cvt_pk_bf16_f32 v147, v160, v147
	v_cvt_pk_bf16_f32 v148, v143, v149
	v_cvt_pk_bf16_f32 v149, v161, v159
	global_store_dwordx4 v[164:165], v[146:149], off offset:256 sc1

.LBB0_247:
	v_mul_f32_e32 v48, 0xbfb8aa3b, v48
	v_mul_f32_e32 v53, 0xbfb8aa3b, v53
	v_exp_f32_e32 v48, v48
	v_exp_f32_e32 v53, v53
	v_mul_f32_e32 v100, 0xbfb8aa3b, v100
	v_mul_f32_e32 v84, 0xbfb8aa3b, v84
	v_mul_f32_e32 v68, 0xbfb8aa3b, v68
	v_mul_f32_e32 v32, 0xbfb8aa3b, v32
	v_mul_f32_e32 v37, 0xbfb8aa3b, v37
	v_exp_f32_e32 v100, v100
	v_exp_f32_e32 v84, v84
	v_exp_f32_e32 v68, v68
	v_exp_f32_e32 v32, v32
	v_exp_f32_e32 v37, v37
	v_mul_f32_e32 v16, 0xbfb8aa3b, v16
	v_mul_f32_e32 v21, 0xbfb8aa3b, v21
	v_add_f32_e32 v48, 1.0, v48
	v_add_f32_e32 v53, 1.0, v53
	v_mul_f32_e32 v49, 0xbfb8aa3b, v49
	v_exp_f32_e32 v16, v16
	v_exp_f32_e32 v21, v21
	v_rcp_f32_e32 v48, v48
	v_rcp_f32_e32 v53, v53
	v_exp_f32_e32 v49, v49
	v_mul_f32_e32 v0, 0xbfb8aa3b, v0
	v_mul_f32_e32 v5, 0xbfb8aa3b, v5
	v_add_f32_e32 v100, 1.0, v100
	v_mul_f32_e32 v96, 0xbfb8aa3b, v96
	v_mul_f32_e32 v101, 0xbfb8aa3b, v101
	v_mul_f32_e32 v97, 0xbfb8aa3b, v97
	v_add_f32_e32 v84, 1.0, v84
	v_mul_f32_e32 v80, 0xbfb8aa3b, v80
	v_mul_f32_e32 v85, 0xbfb8aa3b, v85
	v_mul_f32_e32 v81, 0xbfb8aa3b, v81
	v_add_f32_e32 v68, 1.0, v68
	v_mul_f32_e32 v64, 0xbfb8aa3b, v64
	v_mul_f32_e32 v69, 0xbfb8aa3b, v69
	v_mul_f32_e32 v65, 0xbfb8aa3b, v65
	v_add_f32_e32 v32, 1.0, v32
	v_add_f32_e32 v37, 1.0, v37
	v_mul_f32_e32 v33, 0xbfb8aa3b, v33
	v_exp_f32_e32 v0, v0
	v_exp_f32_e32 v5, v5
	v_exp_f32_e32 v96, v96
	v_exp_f32_e32 v101, v101
	v_rcp_f32_e32 v100, v100
	v_exp_f32_e32 v97, v97
	v_exp_f32_e32 v80, v80
	v_exp_f32_e32 v85, v85
	v_rcp_f32_e32 v84, v84
	v_exp_f32_e32 v81, v81
	v_exp_f32_e32 v64, v64
	v_exp_f32_e32 v69, v69
	v_rcp_f32_e32 v68, v68
	v_exp_f32_e32 v65, v65
	v_rcp_f32_e32 v32, v32
	v_rcp_f32_e32 v37, v37
	v_exp_f32_e32 v33, v33
	v_add_f32_e32 v16, 1.0, v16
	v_add_f32_e32 v21, 1.0, v21
	v_mul_f32_e32 v17, 0xbfb8aa3b, v17
	v_mul_f32_e32 v116, 0xbfb8aa3b, v116
	v_mul_f32_e32 v112, 0xbfb8aa3b, v112
	v_mul_f32_e32 v113, 0xbfb8aa3b, v113
	v_mul_f32_e32 v56, v56, v48
	v_mul_f32_e32 v48, v61, v53
	v_add_f32_e32 v49, 1.0, v49
	v_mul_f32_e32 v53, 0xbfb8aa3b, v54
	v_rcp_f32_e32 v16, v16
	v_rcp_f32_e32 v21, v21
	v_exp_f32_e32 v17, v17
	v_exp_f32_e32 v116, v116
	v_exp_f32_e32 v112, v112
	v_mul_f32_e32 v117, 0xbfb8aa3b, v117
	v_exp_f32_e32 v113, v113
	v_mul_f32_e32 v118, 0xbfb8aa3b, v118
	v_mul_f32_e32 v114, 0xbfb8aa3b, v114
	v_mul_f32_e32 v119, 0xbfb8aa3b, v119
	v_rcp_f32_e32 v49, v49
	v_exp_f32_e32 v53, v53
	v_add_f32_e32 v0, 1.0, v0
	v_add_f32_e32 v5, 1.0, v5
	v_mul_f32_e32 v1, 0xbfb8aa3b, v1
	v_exp_f32_e32 v117, v117
	v_exp_f32_e32 v118, v118
	v_exp_f32_e32 v114, v114
	v_exp_f32_e32 v119, v119
	v_mul_f32_e32 v115, 0xbfb8aa3b, v115
	v_add_f32_e32 v96, 1.0, v96
	v_add_f32_e32 v101, 1.0, v101
	v_mul_f32_e32 v108, v108, v100
	v_add_f32_e32 v97, 1.0, v97
	v_mul_f32_e32 v100, 0xbfb8aa3b, v102
	v_add_f32_e32 v80, 1.0, v80
	v_add_f32_e32 v85, 1.0, v85
	v_mul_f32_e32 v92, v92, v84
	v_add_f32_e32 v81, 1.0, v81
	v_mul_f32_e32 v84, 0xbfb8aa3b, v86
	v_add_f32_e32 v64, 1.0, v64
	v_add_f32_e32 v69, 1.0, v69
	v_mul_f32_e32 v76, v76, v68
	v_add_f32_e32 v65, 1.0, v65
	v_mul_f32_e32 v68, 0xbfb8aa3b, v70
	v_mul_f32_e32 v40, v40, v32
	v_mul_f32_e32 v32, v45, v37
	v_add_f32_e32 v33, 1.0, v33
	v_mul_f32_e32 v37, 0xbfb8aa3b, v38
	v_rcp_f32_e32 v0, v0
	v_rcp_f32_e32 v5, v5
	v_exp_f32_e32 v1, v1
	v_exp_f32_e32 v115, v115
	v_rcp_f32_e32 v96, v96
	v_rcp_f32_e32 v101, v101
	v_rcp_f32_e32 v97, v97
	v_exp_f32_e32 v100, v100
	v_rcp_f32_e32 v80, v80
	v_rcp_f32_e32 v85, v85
	v_rcp_f32_e32 v81, v81
	v_exp_f32_e32 v84, v84
	v_rcp_f32_e32 v64, v64
	v_rcp_f32_e32 v69, v69
	v_rcp_f32_e32 v65, v65
	v_exp_f32_e32 v68, v68
	v_mul_f32_e32 v52, 0xbfb8aa3b, v52
	v_rcp_f32_e32 v33, v33
	v_exp_f32_e32 v37, v37
	v_exp_f32_e32 v52, v52
	v_mul_f32_e32 v24, v24, v16
	v_mul_f32_e32 v16, v29, v21
	v_add_f32_e32 v17, 1.0, v17
	v_mul_f32_e32 v21, 0xbfb8aa3b, v22
	v_add_f32_e32 v116, 1.0, v116
	v_add_f32_e32 v112, 1.0, v112
	v_add_f32_e32 v113, 1.0, v113
	v_mul_f32_e32 v50, 0xbfb8aa3b, v50
	v_mul_f32_e32 v54, v57, v49
	v_add_f32_e32 v49, 1.0, v53
	v_mul_f32_e32 v53, 0xbfb8aa3b, v55
	v_mul_f32_e32 v36, 0xbfb8aa3b, v36
	v_rcp_f32_e32 v17, v17
	v_exp_f32_e32 v21, v21
	v_rcp_f32_e32 v116, v116
	v_rcp_f32_e32 v112, v112
	v_add_f32_e32 v117, 1.0, v117
	v_rcp_f32_e32 v113, v113
	v_add_f32_e32 v118, 1.0, v118
	v_add_f32_e32 v114, 1.0, v114
	v_add_f32_e32 v119, 1.0, v119
	v_exp_f32_e32 v50, v50
	v_exp_f32_e32 v53, v53
	v_exp_f32_e32 v36, v36
	v_mul_f32_e32 v8, v8, v0
	v_mul_f32_e32 v0, v13, v5
	v_add_f32_e32 v1, 1.0, v1
	v_mul_f32_e32 v5, 0xbfb8aa3b, v6
	v_rcp_f32_e32 v117, v117
	v_rcp_f32_e32 v118, v118
	v_rcp_f32_e32 v114, v114
	v_rcp_f32_e32 v119, v119
	v_add_f32_e32 v115, 1.0, v115
	v_mul_f32_e32 v104, v104, v96
	v_mul_f32_e32 v96, v109, v101
	v_mul_f32_e32 v98, 0xbfb8aa3b, v98
	v_mul_f32_e32 v101, v105, v97
	v_add_f32_e32 v97, 1.0, v100
	v_mul_f32_e32 v100, 0xbfb8aa3b, v103
	v_mul_f32_e32 v88, v88, v80
	v_mul_f32_e32 v80, v93, v85
	v_mul_f32_e32 v82, 0xbfb8aa3b, v82
	v_mul_f32_e32 v85, v89, v81
	v_add_f32_e32 v81, 1.0, v84
	v_mul_f32_e32 v84, 0xbfb8aa3b, v87
	v_mul_f32_e32 v72, v72, v64
	v_mul_f32_e32 v64, v77, v69
	v_mul_f32_e32 v66, 0xbfb8aa3b, v66
	v_mul_f32_e32 v69, v73, v65
	v_add_f32_e32 v65, 1.0, v68
	v_mul_f32_e32 v68, 0xbfb8aa3b, v71
	v_mul_f32_e32 v34, 0xbfb8aa3b, v34
	v_mul_f32_e32 v38, v41, v33
	v_add_f32_e32 v33, 1.0, v37
	v_mul_f32_e32 v37, 0xbfb8aa3b, v39
	v_mul_f32_e32 v20, 0xbfb8aa3b, v20
	v_rcp_f32_e32 v1, v1
	v_exp_f32_e32 v5, v5
	v_rcp_f32_e32 v115, v115
	v_exp_f32_e32 v98, v98
	v_exp_f32_e32 v100, v100
	v_exp_f32_e32 v82, v82
	v_exp_f32_e32 v84, v84
	v_exp_f32_e32 v66, v66
	v_exp_f32_e32 v68, v68
	v_add_f32_e32 v52, 1.0, v52
	v_exp_f32_e32 v34, v34
	v_exp_f32_e32 v37, v37
	v_exp_f32_e32 v20, v20
	v_rcp_f32_e32 v52, v52
	v_mul_f32_e32 v18, 0xbfb8aa3b, v18
	v_mul_f32_e32 v22, v25, v17
	v_add_f32_e32 v17, 1.0, v21
	v_mul_f32_e32 v21, 0xbfb8aa3b, v23
	v_mul_f32_e32 v4, 0xbfb8aa3b, v4
	v_lshl_or_b32 v146, s67, 7, v153
	v_mul_f32_e32 v116, v124, v116
	v_mul_f32_e32 v112, v120, v112
	v_mul_f32_e32 v113, v121, v113
	v_ashrrev_i32_e32 v145, 31, v144
	v_add_f32_e32 v50, 1.0, v50
	v_add_f32_e32 v53, 1.0, v53
	v_add_f32_e32 v36, 1.0, v36
	v_exp_f32_e32 v18, v18
	v_exp_f32_e32 v21, v21
	v_exp_f32_e32 v4, v4
	v_ashrrev_i32_e32 v147, 31, v146
	v_mul_f32_e32 v117, v125, v117
	v_mul_f32_e32 v118, v126, v118
	v_mul_f32_e32 v120, v122, v114
	v_mul_f32_e32 v119, v127, v119
	v_cvt_pk_bf16_f32 v114, v116, v117
	v_cvt_pk_bf16_f32 v116, v112, v113
	v_lshlrev_b64 v[112:113], 11, v[144:145]
	v_mul_f32_e32 v99, 0xbfb8aa3b, v99
	v_mul_f32_e32 v83, 0xbfb8aa3b, v83
	v_mul_f32_e32 v67, 0xbfb8aa3b, v67
	v_mul_f32_e32 v51, 0xbfb8aa3b, v51
	v_rcp_f32_e32 v50, v50
	v_rcp_f32_e32 v53, v53
	v_rcp_f32_e32 v36, v36
	v_mul_f32_e32 v35, 0xbfb8aa3b, v35
	v_mul_f32_e32 v19, 0xbfb8aa3b, v19
	v_mul_f32_e32 v2, 0xbfb8aa3b, v2
	v_mul_f32_e32 v6, v9, v1
	v_add_f32_e32 v1, 1.0, v5
	v_mul_f32_e32 v5, 0xbfb8aa3b, v7
	v_mul_f32_e32 v3, 0xbfb8aa3b, v3
	v_mul_f32_e32 v121, v123, v115
	v_cvt_pk_bf16_f32 v115, v118, v119
	v_lshl_add_u64 v[112:113], s[36:37], 0, v[112:113]
	v_lshlrev_b64 v[118:119], 1, v[146:147]
	v_add_f32_e32 v98, 1.0, v98
	v_exp_f32_e32 v99, v99
	v_add_f32_e32 v100, 1.0, v100
	v_add_f32_e32 v82, 1.0, v82
	v_exp_f32_e32 v83, v83
	v_add_f32_e32 v84, 1.0, v84
	v_add_f32_e32 v66, 1.0, v66
	v_exp_f32_e32 v67, v67
	v_add_f32_e32 v68, 1.0, v68
	v_exp_f32_e32 v51, v51
	v_add_f32_e32 v34, 1.0, v34
	v_exp_f32_e32 v35, v35
	v_add_f32_e32 v37, 1.0, v37
	v_add_f32_e32 v20, 1.0, v20
	v_exp_f32_e32 v19, v19
	v_exp_f32_e32 v2, v2
	v_exp_f32_e32 v5, v5
	v_exp_f32_e32 v3, v3
	v_lshl_add_u64 v[112:113], v[112:113], 0, v[118:119]
	v_rcp_f32_e32 v97, v97
	v_rcp_f32_e32 v98, v98
	v_rcp_f32_e32 v100, v100
	v_rcp_f32_e32 v81, v81
	v_rcp_f32_e32 v82, v82
	v_rcp_f32_e32 v84, v84
	v_rcp_f32_e32 v65, v65
	v_rcp_f32_e32 v66, v66
	v_rcp_f32_e32 v68, v68
	v_mul_f32_e32 v52, v60, v52
	v_rcp_f32_e32 v34, v34
	v_rcp_f32_e32 v37, v37
	v_rcp_f32_e32 v20, v20
	v_cvt_pk_bf16_f32 v48, v52, v48
	v_add_co_u32_e32 v52, vcc, s62, v112
	v_add_f32_e32 v18, 1.0, v18
	v_add_f32_e32 v21, 1.0, v21
	v_add_f32_e32 v4, 1.0, v4
	v_mul_f32_e32 v55, v58, v50
	v_mul_f32_e32 v50, v63, v53
	v_addc_co_u32_e32 v53, vcc, 0, v113, vcc
	v_mul_f32_e32 v36, v44, v36
	v_rcp_f32_e32 v18, v18
	v_rcp_f32_e32 v21, v21
	v_rcp_f32_e32 v4, v4
	v_add_f32_e32 v99, 1.0, v99
	v_add_f32_e32 v83, 1.0, v83
	v_add_f32_e32 v67, 1.0, v67
	v_add_f32_e32 v51, 1.0, v51
	v_add_f32_e32 v35, 1.0, v35
	v_cvt_pk_bf16_f32 v32, v36, v32
	v_add_co_u32_e32 v36, vcc, s63, v112
	v_add_f32_e32 v19, 1.0, v19
	v_add_f32_e32 v2, 1.0, v2
	v_add_f32_e32 v5, 1.0, v5
	v_add_f32_e32 v3, 1.0, v3
	v_rcp_f32_e32 v99, v99
	v_mul_f32_e32 v97, v110, v97
	v_mul_f32_e32 v102, v106, v98
	v_mul_f32_e32 v98, v111, v100
	v_or_b32_e32 v100, 16, v144
	v_rcp_f32_e32 v83, v83
	v_mul_f32_e32 v81, v94, v81
	v_mul_f32_e32 v86, v90, v82
	v_mul_f32_e32 v82, v95, v84
	v_or_b32_e32 v84, 32, v144
	v_rcp_f32_e32 v67, v67
	v_mul_f32_e32 v65, v78, v65
	v_mul_f32_e32 v70, v74, v66
	v_mul_f32_e32 v66, v79, v68
	v_or_b32_e32 v68, 48, v144
	v_rcp_f32_e32 v49, v49
	v_rcp_f32_e32 v51, v51
	v_rcp_f32_e32 v33, v33
	v_rcp_f32_e32 v35, v35
	v_mul_f32_e32 v39, v42, v34
	v_mul_f32_e32 v34, v47, v37
	v_addc_co_u32_e32 v37, vcc, 0, v113, vcc
	v_mul_f32_e32 v20, v28, v20
	v_rcp_f32_e32 v17, v17
	v_rcp_f32_e32 v19, v19
	v_rcp_f32_e32 v1, v1
	v_rcp_f32_e32 v2, v2
	v_rcp_f32_e32 v5, v5
	v_rcp_f32_e32 v3, v3
	v_cvt_pk_bf16_f32 v97, v97, v98
	v_cvt_pk_bf16_f32 v98, v104, v101
	v_ashrrev_i32_e32 v101, 31, v100
	v_cvt_pk_bf16_f32 v81, v81, v82
	v_cvt_pk_bf16_f32 v82, v88, v85
	v_ashrrev_i32_e32 v85, 31, v84
	v_cvt_pk_bf16_f32 v65, v65, v66
	v_cvt_pk_bf16_f32 v66, v72, v69
	v_ashrrev_i32_e32 v69, 31, v68
	v_cvt_pk_bf16_f32 v16, v20, v16
	v_add_co_u32_e32 v20, vcc, s64, v112
	v_lshlrev_b64 v[100:101], 11, v[100:101]
	v_lshlrev_b64 v[84:85], 11, v[84:85]
	v_lshlrev_b64 v[68:69], 11, v[68:69]
	v_mul_f32_e32 v23, v26, v18
	v_mul_f32_e32 v18, v31, v21
	v_addc_co_u32_e32 v21, vcc, 0, v113, vcc
	v_mul_f32_e32 v4, v12, v4
	v_lshl_add_u64 v[100:101], s[36:37], 0, v[100:101]
	v_lshl_add_u64 v[84:85], s[36:37], 0, v[84:85]
	v_lshl_add_u64 v[68:69], s[36:37], 0, v[68:69]
	v_cvt_pk_bf16_f32 v0, v4, v0
	v_add_co_u32_e32 v4, vcc, 0x58000, v112
	v_mul_f32_e32 v99, v107, v99
	v_lshl_add_u64 v[100:101], v[100:101], 0, v[118:119]
	v_mul_f32_e32 v83, v91, v83
	v_lshl_add_u64 v[84:85], v[84:85], 0, v[118:119]
	v_mul_f32_e32 v67, v75, v67
	v_lshl_add_u64 v[68:69], v[68:69], 0, v[118:119]
	v_mul_f32_e32 v49, v62, v49
	v_mul_f32_e32 v51, v59, v51
	v_mul_f32_e32 v33, v46, v33
	v_mul_f32_e32 v35, v43, v35
	v_mul_f32_e32 v17, v30, v17
	v_mul_f32_e32 v19, v27, v19
	v_mul_f32_e32 v1, v14, v1
	v_mul_f32_e32 v7, v10, v2
	v_mul_f32_e32 v2, v15, v5
	v_mul_f32_e32 v3, v11, v3
	v_addc_co_u32_e32 v5, vcc, 0, v113, vcc
	v_cvt_pk_bf16_f32 v117, v120, v121
	global_store_dwordx4 v[112:113], v[114:117], off sc1
	v_cvt_pk_bf16_f32 v96, v108, v96
	v_cvt_pk_bf16_f32 v99, v102, v99
	global_store_dwordx4 v[100:101], v[96:99], off sc1
	v_cvt_pk_bf16_f32 v80, v92, v80
	v_cvt_pk_bf16_f32 v83, v86, v83
	global_store_dwordx4 v[84:85], v[80:83], off sc1
	v_cvt_pk_bf16_f32 v64, v76, v64
	v_cvt_pk_bf16_f32 v67, v70, v67
	global_store_dwordx4 v[68:69], v[64:67], off sc1
	v_cvt_pk_bf16_f32 v49, v49, v50
	v_cvt_pk_bf16_f32 v50, v56, v54
	v_cvt_pk_bf16_f32 v51, v55, v51
	global_store_dwordx4 v[52:53], v[48:51], off sc1
	v_cvt_pk_bf16_f32 v33, v33, v34
	v_cvt_pk_bf16_f32 v34, v40, v38
	v_cvt_pk_bf16_f32 v35, v39, v35
	global_store_dwordx4 v[36:37], v[32:35], off sc1
	v_cvt_pk_bf16_f32 v17, v17, v18
	v_cvt_pk_bf16_f32 v18, v24, v22
	v_cvt_pk_bf16_f32 v19, v23, v19
	global_store_dwordx4 v[20:21], v[16:19], off sc1
	v_cvt_pk_bf16_f32 v1, v1, v2
	v_cvt_pk_bf16_f32 v2, v8, v6
	v_cvt_pk_bf16_f32 v3, v7, v3
	global_store_dwordx4 v[4:5], v[0:3], off sc1
	s_branch .LBB0_235
